# P3: u rows requested two groups ahead (two u register sets, loop unrolled by two)
# baseline (speedup 1.0000x reference)
; __device__ __forceinline__ float bf_lo(unsigned u) { return __uint_as_float(u << 16); }
; __device__ __forceinline__ float bf_hi(unsigned u) { return __uint_as_float(u & 0xffff0000u); }
; __device__ __forceinline__ void p3_token(const Params& p, int tok, int lane, unsigned* rec, float& sh, int& hs8) {
;     const bf16_t* H = (const bf16_t*)(p.ws + OFF_H);
;     const int* eidx = (const int*)(p.ws + OFF_EIDX);
;     const float* gwp = (const float*)(p.ws + OFF_GW);
;     {
;         const u32x4 a = *(const u32x4*)(H + (size_t)tok * DM + lane * 16), b = *(const u32x4*)(H + (size_t)tok * DM + lane * 16 + 8);
;         const unsigned hw[8] = {a.x, a.y, a.z, a.w, b.x, b.y, b.z, b.w};
;         float hv[16];
;         float mx = 0.f;
; #pragma unroll
;         for (int i = 0; i < 8; i++) { hv[2 * i] = bf_lo(hw[i]); hv[2 * i + 1] = bf_hi(hw[i]); mx = fmaxf(mx, fmaxf(fabsf(hv[2 * i]), fabsf(hv[2 * i + 1]))); }
;         mx = wave_max(mx);
;         const float inv = mx > 0.f ? 119.f / mx : 0.f;
;         sh = mx * (1.f / 119.f);
;         unsigned qh[4] = {0u, 0u, 0u, 0u};
; #pragma unroll
;         for (int e = 0; e < 16; e++) {
;             const int qi = (int)rintf(hv[e] * inv);
;             const int hh = (qi + 8) >> 4, hl = qi - 16 * hh;
;             qh[(e >> 3) * 2] |= (unsigned)(hh & 15) << ((e & 7) * 4);
;             qh[(e >> 3) * 2 + 1] |= (unsigned)(hl & 15) << ((e & 7) * 4);
;         }
.LBB0_1042:
	v_ashrrev_i32_e32 v9, 31, v8
	s_waitcnt vmcnt(0)
	v_lshlrev_b64 v[28:29], 11, v[8:9]
	v_lshl_add_u64 v[30:31], v[20:21], 0, v[28:29]
	global_load_dwordx4 v[0:3], v[30:31], off
	global_load_dwordx4 v[4:7], v[30:31], off offset:16
	s_waitcnt vmcnt(1)
	v_lshlrev_b32_e32 v12, 16, v0
	v_and_b32_e32 v27, 0xffff0000, v0
	v_lshlrev_b32_e32 v36, 16, v1
	v_and_b32_e32 v37, 0xffff0000, v1
	v_lshlrev_b32_e32 v38, 16, v2
	v_and_b32_e32 v39, 0xffff0000, v2
	v_lshlrev_b32_e32 v40, 16, v3
	v_and_b32_e32 v41, 0xffff0000, v3
	v_max_f32_e64 v0, |v27|, |v27|
	v_max_f32_e64 v1, |v12|, |v12|
	v_max_f32_e64 v2, |v37|, |v37|
	v_max_f32_e64 v3, |v36|, |v36|
	s_waitcnt vmcnt(0)
	v_lshlrev_b32_e32 v42, 16, v4
	v_and_b32_e32 v43, 0xffff0000, v4
	v_lshlrev_b32_e32 v44, 16, v5
	v_and_b32_e32 v5, 0xffff0000, v5
	v_lshlrev_b32_e32 v45, 16, v6
	v_and_b32_e32 v46, 0xffff0000, v6
	v_lshlrev_b32_e32 v47, 16, v7
	v_and_b32_e32 v48, 0xffff0000, v7
	v_max_f32_e64 v4, |v39|, |v39|
	v_max_f32_e64 v6, |v38|, |v38|
	v_max_f32_e64 v7, |v41|, |v41|
	v_max_f32_e64 v30, |v40|, |v40|
	v_max_f32_e32 v0, v1, v0
	v_max_f32_e32 v1, v3, v2
	v_max_f32_e64 v31, |v43|, |v43|
	v_max_f32_e64 v32, |v42|, |v42|
	v_max_f32_e64 v33, |v5|, |v5|
	v_max_f32_e64 v34, |v44|, |v44|
	v_max_f32_e32 v2, v6, v4
	v_max_f32_e32 v3, v30, v7
	v_max3_f32 v0, v0, 0, v1
	v_max_f32_e64 v35, |v46|, |v46|
	v_max_f32_e64 v49, |v45|, |v45|
	v_max_f32_e64 v50, |v48|, |v48|
	v_max_f32_e64 v51, |v47|, |v47|
	v_max_f32_e32 v4, v32, v31
	v_max_f32_e32 v6, v34, v33
	v_max3_f32 v0, v0, v2, v3
	v_max_f32_e32 v7, v49, v35
	v_max_f32_e32 v30, v51, v50
	v_max3_f32 v0, v0, v4, v6
	v_max3_f32 v0, v0, v7, v30
	ds_bpermute_b32 v1, v112, v0
	s_waitcnt lgkmcnt(0)
	v_max_f32_e32 v1, v1, v1
	v_max_f32_e32 v0, v0, v1
	ds_bpermute_b32 v1, v113, v0
	s_waitcnt lgkmcnt(0)
	v_max_f32_e32 v1, v1, v1
	v_max_f32_e32 v0, v0, v1
	ds_bpermute_b32 v1, v114, v0
	s_waitcnt lgkmcnt(0)
	v_max_f32_e32 v1, v1, v1
	v_max_f32_e32 v0, v0, v1
	ds_bpermute_b32 v1, v115, v0
	s_waitcnt lgkmcnt(0)
	v_max_f32_e32 v1, v1, v1
	v_max_f32_e32 v2, v0, v1
	ds_bpermute_b32 v4, v116, v2
	v_lshlrev_b64 v[0:1], 9, v[8:9]
	v_lshl_or_b32 v0, v10, 2, v0
	v_mov_b32_e32 v3, v1
	v_lshl_add_u64 v[6:7], s[20:21], 0, v[0:1]
	s_waitcnt lgkmcnt(0)
	v_max_f32_e32 v4, v4, v4
	v_max_f32_e32 v4, v2, v4
	ds_bpermute_b32 v49, v117, v4
	v_or_b32_e32 v2, 0x100, v0
	v_lshl_add_u64 v[30:31], s[24:25], 0, v[0:1]
	v_lshl_add_u64 v[32:33], s[20:21], 0, v[2:3]
	v_lshl_add_u64 v[34:35], s[24:25], 0, v[2:3]
	s_waitcnt lgkmcnt(0)
	v_max_f32_e32 v0, v49, v49
	v_max_f32_e32 v0, v4, v0
	global_load_dword v4, v[6:7], off
	global_load_dword v1, v[32:33], off
	global_load_dword v2, v[30:31], off
	global_load_dword v3, v[34:35], off
	v_div_scale_f32 v49, s[4:5], v0, v0, s33
	v_rcp_f32_e32 v50, v49
	v_div_scale_f32 v6, vcc, s33, v0, s33
	v_fma_f32 v7, -v49, v50, 1.0
	v_fmac_f32_e32 v50, v7, v50
	v_mul_f32_e32 v7, v6, v50
	v_fma_f32 v30, -v49, v7, v6
	v_fmac_f32_e32 v7, v30, v50
	v_fma_f32 v6, -v49, v7, v6
	v_div_fmas_f32 v6, v6, v50, v7
	v_div_fixup_f32 v6, v6, v0, s33
	v_cmp_lt_f32_e32 vcc, 0, v0
	s_waitcnt vmcnt(2)
	v_cmp_gt_u32_e64 s[4:5], s37, v1
	v_cndmask_b32_e32 v6, 0, v6, vcc
	v_mul_f32_e32 v7, v6, v12
	v_mul_f32_e32 v12, v6, v27
	v_mul_f32_e32 v27, v6, v36
	v_mul_f32_e32 v30, v6, v37
	v_rndne_f32_e32 v7, v7
	v_rndne_f32_e32 v12, v12
	v_mul_f32_e32 v31, v6, v38
	v_mul_f32_e32 v32, v6, v39
	v_mul_f32_e32 v34, v6, v41
	v_rndne_f32_e32 v27, v27
	v_rndne_f32_e32 v30, v30
	v_cvt_i32_f32_e32 v7, v7
	v_cvt_i32_f32_e32 v12, v12
	v_mul_f32_e32 v33, v6, v40
	v_rndne_f32_e32 v31, v31
	v_rndne_f32_e32 v32, v32
	v_rndne_f32_e32 v34, v34
	v_cvt_i32_f32_e32 v27, v27
	v_cvt_i32_f32_e32 v30, v30
	v_rndne_f32_e32 v33, v33
	v_cvt_i32_f32_e32 v31, v31
	v_cvt_i32_f32_e32 v32, v32
	v_cvt_i32_f32_e32 v34, v34
	v_cvt_i32_f32_e32 v33, v33
	v_add_u32_e32 v36, 8, v7
	v_add_u32_e32 v37, 8, v12
	v_and_b32_e32 v7, 15, v7
	v_lshlrev_b32_e32 v12, 4, v12
	v_lshl_add_u32 v38, v27, 4, v122
	v_lshlrev_b32_e32 v27, 8, v27
	v_lshl_add_u32 v39, v30, 8, v123
	v_lshrrev_b32_e32 v36, 4, v36
	v_and_b32_e32 v37, 0xf0, v37
	v_lshl_add_u32 v40, v31, 12, v124
	v_lshl_add_u32 v41, v32, 16, v125
	v_lshl_add_u32 v49, v34, 24, v127
	v_and_b32_e32 v12, 0xf0, v12
	v_and_b32_e32 v38, 0xf00, v38
	v_and_b32_e32 v27, 0xf00, v27
	v_and_b32_e32 v39, 0xf000, v39
	v_lshl_or_b32 v7, v34, 28, v7
	v_and_or_b32 v34, v36, 15, v37
	v_mul_f32_e32 v35, v6, v42
	v_lshlrev_b32_e32 v30, 12, v30
	v_lshlrev_b32_e32 v31, 16, v31
	v_lshl_add_u32 v42, v33, 20, v126
	v_and_b32_e32 v40, 0xf0000, v40
	v_and_b32_e32 v41, 0xf00000, v41
	v_or3_b32 v7, v7, v12, v27
	v_or3_b32 v12, v34, v38, v39
	v_and_b32_e32 v30, 0xf000, v30
	v_and_b32_e32 v31, 0xf0000, v31
	v_and_b32_e32 v42, 0xf000000, v42
	v_and_b32_e32 v49, 0xf0000000, v49
	v_or3_b32 v12, v12, v40, v41
	v_lshlrev_b32_e32 v32, 20, v32
	v_lshlrev_b32_e32 v33, 24, v33
	v_or3_b32 v7, v7, v30, v31
	v_or3_b32 v30, v12, v42, v49
	v_mul_f32_e32 v12, v6, v43
	v_rndne_f32_e32 v35, v35
	v_and_b32_e32 v32, 0xf00000, v32
	v_and_b32_e32 v33, 0xf000000, v33
	v_rndne_f32_e32 v12, v12
	v_or3_b32 v31, v7, v32, v33
	v_cvt_i32_f32_e32 v7, v35
	v_cvt_i32_f32_e32 v12, v12
	v_mul_f32_e32 v33, v6, v44
	v_mul_f32_e32 v5, v6, v5
	v_rndne_f32_e32 v33, v33
	v_rndne_f32_e32 v5, v5
	v_cvt_i32_f32_e32 v33, v33
	v_cvt_i32_f32_e32 v5, v5
	v_add_u32_e32 v27, 8, v7
	v_add_u32_e32 v32, 8, v12
	v_lshrrev_b32_e32 v27, 4, v27
	v_and_b32_e32 v32, 0xf0, v32
	v_and_or_b32 v27, v27, 15, v32
	v_lshl_add_u32 v32, v33, 4, v122
	v_lshl_add_u32 v34, v5, 8, v123
	v_and_b32_e32 v32, 0xf00, v32
	v_and_b32_e32 v34, 0xf000, v34
	v_mul_f32_e32 v35, v6, v45
; __device__ __forceinline__ void p3_token(const Params& p, int tok, int lane, unsigned* rec, float& sh, int& hs8) {
;     ...
;         unsigned qh[4] = {0u, 0u, 0u, 0u};
; #pragma unroll
;         for (int e = 0; e < 16; e++) {
;             const int qi = (int)rintf(hv[e] * inv);
;             const int hh = (qi + 8) >> 4, hl = qi - 16 * hh;
;             qh[(e >> 3) * 2] |= (unsigned)(hh & 15) << ((e & 7) * 4);
;             qh[(e >> 3) * 2 + 1] |= (unsigned)(hl & 15) << ((e & 7) * 4);
;         }
;         hs8 = 0;
;         *(u32x4*)(rec + 256 + lane * 4) = (u32x4){qh[0], qh[1], qh[2], qh[3]};
;     }
;     const int e0 = eidx[(size_t)tok * 128 + lane], e1 = eidx[(size_t)tok * 128 + 64 + lane];
;     const float g0 = gwp[(size_t)tok * 128 + lane], g1 = gwp[(size_t)tok * 128 + 64 + lane];
;     const int k0 = e0 >> 11, k1 = e1 >> 11;
;     int pos0 = 0, pos1 = 0, base = 0;
; #pragma unroll
;     for (int v = 0; v < 8; v++) {
;         const unsigned long long m0 = __ballot(k0 == v), m1 = __ballot(k1 == v);
;         const int c0 = __popcll(m0);
;         const int r0 = __builtin_amdgcn_mbcnt_hi((unsigned)(m0 >> 32), __builtin_amdgcn_mbcnt_lo((unsigned)m0, 0u));
;         const int r1 = __builtin_amdgcn_mbcnt_hi((unsigned)(m1 >> 32), __builtin_amdgcn_mbcnt_lo((unsigned)m1, 0u));
;         pos0 = (k0 == v) ? base + r0 : pos0;
;         pos1 = (k1 == v) ? base + c0 + r1 : pos1;
;         base += c0 + __popcll(m1);
;     }
;     const float* tsc = (const float*)(p.ws + OFF_UB + 33554432);
;     const f32x2 s0 = *(const f32x2*)(tsc + 2 * e0), s1 = *(const f32x2*)(tsc + 2 * e1);
	v_or3_b32 v27, v27, v32, v34
	v_mul_f32_e32 v34, v6, v46
	v_rndne_f32_e32 v35, v35
	v_rndne_f32_e32 v34, v34
	v_cvt_i32_f32_e32 v35, v35
	v_cvt_i32_f32_e32 v34, v34
	v_mul_f32_e32 v37, v6, v47
	v_mul_f32_e32 v6, v6, v48
	v_rndne_f32_e32 v37, v37
	v_rndne_f32_e32 v6, v6
	v_cvt_i32_f32_e32 v37, v37
	v_cvt_i32_f32_e32 v6, v6
	v_lshl_add_u32 v32, v35, 12, v124
	v_lshl_add_u32 v36, v34, 16, v125
	v_and_b32_e32 v32, 0xf0000, v32
	v_and_b32_e32 v36, 0xf00000, v36
	v_and_b32_e32 v7, 15, v7
	v_lshlrev_b32_e32 v12, 4, v12
	v_lshlrev_b32_e32 v33, 8, v33
	v_or3_b32 v27, v27, v32, v36
	v_lshlrev_b32_e32 v32, 20, v34
	v_and_b32_e32 v12, 0xf0, v12
	v_and_b32_e32 v33, 0xf00, v33
	v_lshlrev_b32_e32 v5, 12, v5
	v_lshlrev_b32_e32 v35, 16, v35
	v_and_b32_e32 v34, 0xf00000, v32
	v_lshl_add_u32 v32, v37, 20, v126
	v_lshlrev_b32_e32 v36, 24, v37
	v_lshl_add_u32 v37, v6, 24, v127
	v_lshl_or_b32 v6, v6, 28, v7
	v_and_b32_e32 v5, 0xf000, v5
	v_and_b32_e32 v35, 0xf0000, v35
	v_or3_b32 v6, v6, v12, v33
	v_and_b32_e32 v32, 0xf000000, v32
	v_and_b32_e32 v36, 0xf000000, v36
	v_and_b32_e32 v37, 0xf0000000, v37
	v_or3_b32 v5, v6, v5, v35
	v_cmp_gt_u32_e32 vcc, s37, v4
	v_or3_b32 v32, v27, v32, v37
	v_or3_b32 v33, v5, v34, v36
	s_bcnt1_i32_b64 s8, vcc
	v_mov_b32_e32 v5, v13
	ds_write_b128 v128, v[30:33] offset:1024
	s_and_saveexec_b64 s[6:7], s[4:5]
	v_mbcnt_lo_u32_b32 v5, s4, 0
	v_mbcnt_hi_u32_b32 v5, s5, v5
	v_add_u32_e32 v5, s8, v5
	s_or_b64 exec, exec, s[6:7]
	v_ashrrev_i32_e32 v6, 11, v4
	s_bcnt1_i32_b64 s42, s[4:5]
	v_cmp_eq_u32_e64 s[4:5], 1, v6
	v_ashrrev_i32_e32 v7, 11, v1
	s_add_i32 s42, s42, s8
	s_bcnt1_i32_b64 s8, s[4:5]
	v_cmp_eq_u32_e64 s[6:7], 1, v7
	s_add_i32 s43, s42, s8
	s_and_saveexec_b64 s[8:9], s[6:7]
	v_mbcnt_lo_u32_b32 v5, s6, 0
	v_mbcnt_hi_u32_b32 v5, s7, v5
	v_add_u32_e32 v5, s43, v5
	s_or_b64 exec, exec, s[8:9]
	s_bcnt1_i32_b64 s6, s[6:7]
	s_add_i32 s43, s43, s6
	v_cmp_eq_u32_e64 s[6:7], 2, v6
	s_bcnt1_i32_b64 s10, s[6:7]
	v_cmp_eq_u32_e64 s[8:9], 2, v7
	s_add_i32 s44, s43, s10
	s_and_saveexec_b64 s[10:11], s[8:9]
	v_mbcnt_lo_u32_b32 v5, s8, 0
	v_mbcnt_hi_u32_b32 v5, s9, v5
	v_add_u32_e32 v5, s44, v5
	s_or_b64 exec, exec, s[10:11]
	s_bcnt1_i32_b64 s8, s[8:9]
	s_add_i32 s44, s44, s8
	v_cmp_eq_u32_e64 s[8:9], 3, v6
	s_bcnt1_i32_b64 s12, s[8:9]
	v_cmp_eq_u32_e64 s[10:11], 3, v7
	s_add_i32 s45, s44, s12
	s_and_saveexec_b64 s[12:13], s[10:11]
	v_mbcnt_lo_u32_b32 v5, s10, 0
	v_mbcnt_hi_u32_b32 v5, s11, v5
	v_add_u32_e32 v5, s45, v5
	s_or_b64 exec, exec, s[12:13]
	s_bcnt1_i32_b64 s10, s[10:11]
	s_add_i32 s45, s45, s10
	v_cmp_eq_u32_e64 s[10:11], 4, v6
	s_bcnt1_i32_b64 s14, s[10:11]
	v_cmp_eq_u32_e64 s[12:13], 4, v7
	s_add_i32 s46, s45, s14
	s_and_saveexec_b64 s[14:15], s[12:13]
	v_mbcnt_lo_u32_b32 v5, s12, 0
	v_mbcnt_hi_u32_b32 v5, s13, v5
	v_add_u32_e32 v5, s46, v5
	s_or_b64 exec, exec, s[14:15]
	s_bcnt1_i32_b64 s12, s[12:13]
	s_add_i32 s46, s46, s12
	v_cmp_eq_u32_e64 s[12:13], 5, v6
	s_bcnt1_i32_b64 s16, s[12:13]
	v_cmp_eq_u32_e64 s[14:15], 5, v7
	s_add_i32 s47, s46, s16
	s_and_saveexec_b64 s[16:17], s[14:15]
	v_mbcnt_lo_u32_b32 v5, s14, 0
	v_mbcnt_hi_u32_b32 v5, s15, v5
	v_add_u32_e32 v5, s47, v5
	s_or_b64 exec, exec, s[16:17]
	s_bcnt1_i32_b64 s14, s[14:15]
	s_add_i32 s47, s47, s14
	v_cmp_eq_u32_e64 s[14:15], 6, v6
	s_bcnt1_i32_b64 s18, s[14:15]
	v_cmp_eq_u32_e64 s[16:17], 6, v7
	s_add_i32 s48, s47, s18
	s_and_saveexec_b64 s[18:19], s[16:17]
	v_mbcnt_lo_u32_b32 v5, s16, 0
	v_mbcnt_hi_u32_b32 v5, s17, v5
	v_add_u32_e32 v5, s48, v5
	s_or_b64 exec, exec, s[18:19]
	s_bcnt1_i32_b64 s16, s[16:17]
	s_add_i32 s48, s48, s16
	v_cmp_eq_u32_e64 s[16:17], 7, v6
	v_cmp_eq_u32_e64 s[18:19], 7, v7
	s_and_saveexec_b64 s[34:35], s[18:19]
	s_bcnt1_i32_b64 s49, s[16:17]
	v_mbcnt_lo_u32_b32 v5, s18, 0
	s_add_i32 s49, s48, s49
	v_mbcnt_hi_u32_b32 v5, s19, v5
	v_add_u32_e32 v5, s49, v5
	s_or_b64 exec, exec, s[34:35]
	v_or_b32_e32 v30, 1, v8
	v_ashrrev_i32_e32 v31, 31, v30
	v_lshlrev_b64 v[32:33], 11, v[30:31]
	v_lshl_add_u64 v[6:7], v[20:21], 0, v[32:33]
	global_load_dwordx4 v[34:37], v[6:7], off
	global_load_dwordx4 v[38:41], v[6:7], off offset:16
	v_mbcnt_lo_u32_b32 v7, s16, 0
	v_lshlrev_b32_e32 v6, 1, v4
	v_mbcnt_lo_u32_b32 v43, s12, 0
	v_lshlrev_b32_e32 v42, 1, v1
	v_mbcnt_hi_u32_b32 v51, s17, v7
	v_ashrrev_i32_e32 v7, 31, v6
	v_mbcnt_lo_u32_b32 v44, s10, 0
	v_mbcnt_lo_u32_b32 v45, s8, 0
	v_mbcnt_hi_u32_b32 v52, s13, v43
	v_ashrrev_i32_e32 v43, 31, v42
	v_lshl_add_u64 v[6:7], v[6:7], 2, s[26:27]
	v_mbcnt_hi_u32_b32 v53, s11, v44
	v_mbcnt_hi_u32_b32 v54, s9, v45
	v_lshl_add_u64 v[42:43], v[42:43], 2, s[26:27]
	global_load_dwordx2 v[44:45], v[6:7], off
	global_load_dwordx2 v[46:47], v[42:43], off
	v_mbcnt_lo_u32_b32 v48, s6, 0
	v_mbcnt_lo_u32_b32 v49, s4, 0
	v_mbcnt_lo_u32_b32 v50, vcc_lo, 0
	v_mbcnt_hi_u32_b32 v6, s7, v48
	v_mbcnt_hi_u32_b32 v7, s5, v49
	v_mbcnt_hi_u32_b32 v42, vcc_hi, v50
	v_add_u32_e32 v43, s48, v51
	v_add_u32_e32 v7, s42, v7
	v_cndmask_b32_e32 v42, 0, v42, vcc
	v_add_u32_e32 v6, s43, v6
	v_cndmask_b32_e64 v7, v42, v7, s[4:5]
	v_cndmask_b32_e64 v6, v7, v6, s[6:7]
	v_mbcnt_lo_u32_b32 v27, s14, 0
	v_mbcnt_hi_u32_b32 v27, s15, v27
	v_add_u32_e32 v27, s47, v27
	v_lshl_add_u32 v5, v5, 2, v11
	v_mul_f32_e32 v12, 0x3c09ae41, v0
	v_mov_b32_e32 v0, 0
	s_waitcnt vmcnt(3)
	v_lshlrev_b32_e32 v48, 16, v34
	v_and_b32_e32 v34, 0xffff0000, v34
	v_lshlrev_b32_e32 v49, 16, v35
	v_and_b32_e32 v35, 0xffff0000, v35
	v_lshlrev_b32_e32 v50, 16, v36
	v_and_b32_e32 v36, 0xffff0000, v36
	v_lshlrev_b32_e32 v51, 16, v37
	v_and_b32_e32 v55, 0xffff0000, v37
	s_waitcnt vmcnt(2)
; __device__ __forceinline__ float bf_lo(unsigned u) { return __uint_as_float(u << 16); }
; __device__ __forceinline__ float bf_hi(unsigned u) { return __uint_as_float(u & 0xffff0000u); }
; __device__ __forceinline__ void p3_token(const Params& p, int tok, int lane, unsigned* rec, float& sh, int& hs8) {
;     ...
;         const u32x4 a = *(const u32x4*)(H + (size_t)tok * DM + lane * 16), b = *(const u32x4*)(H + (size_t)tok * DM + lane * 16 + 8);
;         const unsigned hw[8] = {a.x, a.y, a.z, a.w, b.x, b.y, b.z, b.w};
;         float hv[16];
;         float mx = 0.f;
; #pragma unroll
;         for (int i = 0; i < 8; i++) { hv[2 * i] = bf_lo(hw[i]); hv[2 * i + 1] = bf_hi(hw[i]); mx = fmaxf(mx, fmaxf(fabsf(hv[2 * i]), fabsf(hv[2 * i + 1]))); }
;         mx = wave_max(mx);
;         const float inv = mx > 0.f ? 119.f / mx : 0.f;
;         sh = mx * (1.f / 119.f);
;         unsigned qh[4] = {0u, 0u, 0u, 0u};
; #pragma unroll
;         for (int e = 0; e < 16; e++) {
;             const int qi = (int)rintf(hv[e] * inv);
;             const int hh = (qi + 8) >> 4, hl = qi - 16 * hh;
;             qh[(e >> 3) * 2] |= (unsigned)(hh & 15) << ((e & 7) * 4);
;             qh[(e >> 3) * 2 + 1] |= (unsigned)(hl & 15) << ((e & 7) * 4);
;         }
;         hs8 = 0;
;         *(u32x4*)(rec + 256 + lane * 4) = (u32x4){qh[0], qh[1], qh[2], qh[3]};
;     }
;     const int e0 = eidx[(size_t)tok * 128 + lane], e1 = eidx[(size_t)tok * 128 + 64 + lane];
;     const float g0 = gwp[(size_t)tok * 128 + lane], g1 = gwp[(size_t)tok * 128 + 64 + lane];
	v_lshlrev_b32_e32 v56, 16, v38
	v_and_b32_e32 v57, 0xffff0000, v38
	v_lshlrev_b32_e32 v58, 16, v39
	v_and_b32_e32 v59, 0xffff0000, v39
	v_max_f32_e64 v37, |v34|, |v34|
	v_max_f32_e64 v38, |v48|, |v48|
	v_max_f32_e64 v39, |v35|, |v35|
	v_max_f32_e64 v62, |v49|, |v49|
	v_max_f32_e64 v63, |v36|, |v36|
	v_max_f32_e64 v64, |v50|, |v50|
	v_max_f32_e64 v65, |v55|, |v55|
	v_max_f32_e64 v66, |v51|, |v51|
	v_max_f32_e32 v37, v38, v37
	v_max_f32_e32 v38, v62, v39
	v_lshlrev_b32_e32 v60, 16, v40
	v_and_b32_e32 v40, 0xffff0000, v40
	v_lshlrev_b32_e32 v61, 16, v41
	v_and_b32_e32 v41, 0xffff0000, v41
	v_max_f32_e64 v67, |v57|, |v57|
	v_max_f32_e64 v68, |v56|, |v56|
	v_max_f32_e64 v69, |v59|, |v59|
	v_max_f32_e64 v70, |v58|, |v58|
	v_max_f32_e32 v39, v64, v63
	v_max_f32_e32 v62, v66, v65
	v_max3_f32 v37, v37, 0, v38
	v_max_f32_e64 v71, |v40|, |v40|
	v_max_f32_e64 v72, |v60|, |v60|
	v_max_f32_e64 v73, |v41|, |v41|
	v_max_f32_e64 v74, |v61|, |v61|
	v_max_f32_e32 v63, v68, v67
	v_max_f32_e32 v64, v70, v69
	v_max3_f32 v37, v37, v39, v62
	v_max_f32_e32 v65, v72, v71
	v_max_f32_e32 v66, v74, v73
	v_max3_f32 v37, v37, v63, v64
	v_max3_f32 v37, v37, v65, v66
	ds_bpermute_b32 v38, v112, v37
	v_add_u32_e32 v39, s46, v52
	v_add_u32_e32 v52, s45, v53
	v_add_u32_e32 v53, s44, v54
	v_cndmask_b32_e64 v6, v6, v53, s[8:9]
	s_waitcnt lgkmcnt(0)
	v_max_f32_e32 v38, v38, v38
	v_max_f32_e32 v37, v37, v38
	ds_bpermute_b32 v38, v113, v37
	v_cndmask_b32_e64 v6, v6, v52, s[10:11]
	v_cndmask_b32_e64 v6, v6, v39, s[12:13]
	v_cndmask_b32_e64 v6, v6, v27, s[14:15]
	v_cndmask_b32_e64 v6, v6, v43, s[16:17]
	s_waitcnt lgkmcnt(0)
	v_max_f32_e32 v38, v38, v38
	v_max_f32_e32 v37, v37, v38
	ds_bpermute_b32 v38, v114, v37
	v_lshl_add_u32 v6, v6, 2, v11
	ds_write_b32 v6, v4
	ds_write_b32 v5, v1
	s_waitcnt vmcnt(1)
	v_mul_f32_e32 v1, v2, v45
	s_waitcnt lgkmcnt(2)
	v_max_f32_e32 v7, v38, v38
	v_max_f32_e32 v7, v37, v7
	ds_bpermute_b32 v37, v115, v7
	s_waitcnt vmcnt(0)
	v_mul_f32_e32 v2, v3, v47
	v_mul_f32_e32 v3, v12, v44
	ds_write_b32 v6, v1 offset:512
	ds_write_b32 v5, v2 offset:512
	ds_write_b32 v6, v3 offset:2048
	v_mul_f32_e32 v12, v12, v46
	s_waitcnt lgkmcnt(3)
	v_max_f32_e32 v4, v37, v37
	v_max_f32_e32 v4, v7, v4
	ds_bpermute_b32 v7, v116, v4
	ds_write_b32 v5, v12 offset:2048
	s_waitcnt lgkmcnt(1)
	v_max_f32_e32 v7, v7, v7
	v_max_f32_e32 v4, v4, v7
	ds_bpermute_b32 v7, v117, v4
	s_waitcnt lgkmcnt(0)
	v_max_f32_e32 v1, v7, v7
	v_max_f32_e32 v1, v4, v1
	v_div_scale_f32 v2, s[4:5], v1, v1, s33
	v_rcp_f32_e32 v3, v2
	v_div_scale_f32 v4, vcc, s33, v1, s33
	v_fma_f32 v5, -v2, v3, 1.0
	v_fmac_f32_e32 v3, v5, v3
	v_mul_f32_e32 v5, v4, v3
	v_fma_f32 v6, -v2, v5, v4
	v_fmac_f32_e32 v5, v6, v3
	v_fma_f32 v2, -v2, v5, v4
	v_div_fmas_f32 v2, v2, v3, v5
	v_div_fixup_f32 v2, v2, v1, s33
	v_cmp_lt_f32_e32 vcc, 0, v1
	s_nop 1
	v_cndmask_b32_e32 v12, 0, v2, vcc
	v_mul_f32_e32 v2, v12, v48
	v_mul_f32_e32 v3, v12, v34
	v_rndne_f32_e32 v2, v2
	v_rndne_f32_e32 v3, v3
	v_cvt_i32_f32_e32 v2, v2
	v_cvt_i32_f32_e32 v3, v3
	v_mul_f32_e32 v4, v12, v49
	v_mul_f32_e32 v5, v12, v35
	v_rndne_f32_e32 v4, v4
	v_add_u32_e32 v6, 8, v2
	v_and_b32_e32 v27, 15, v2
	v_add_u32_e32 v2, 8, v3
	v_lshlrev_b32_e32 v3, 4, v3
	v_cvt_i32_f32_e32 v4, v4
	v_and_b32_e32 v42, 0xf0, v3
	v_rndne_f32_e32 v3, v5
	v_cvt_i32_f32_e32 v3, v3
	v_lshl_add_u32 v7, v4, 4, v122
	v_lshlrev_b32_e32 v4, 8, v4
	v_lshrrev_b32_e32 v6, 4, v6
	v_and_b32_e32 v2, 0xf0, v2
	v_and_b32_e32 v43, 0xf00, v4
	v_lshl_add_u32 v4, v3, 8, v123
	v_and_or_b32 v2, v6, 15, v2
	v_and_b32_e32 v5, 0xf00, v7
	v_and_b32_e32 v4, 0xf000, v4
	v_mul_f32_e32 v6, v12, v50
	v_rndne_f32_e32 v6, v6
	v_or3_b32 v2, v2, v5, v4
	v_mul_f32_e32 v4, v12, v36
	v_cvt_i32_f32_e32 v6, v6
	v_rndne_f32_e32 v4, v4
	v_cvt_i32_f32_e32 v4, v4
	v_lshlrev_b32_e32 v3, 12, v3
	v_lshlrev_b32_e32 v5, 16, v6
	v_and_b32_e32 v44, 0xf000, v3
	v_lshl_add_u32 v3, v6, 12, v124
	v_and_b32_e32 v45, 0xf0000, v5
	v_lshl_add_u32 v5, v4, 16, v125
	v_and_b32_e32 v3, 0xf0000, v3
	v_and_b32_e32 v5, 0xf00000, v5
	v_or3_b32 v46, v2, v3, v5
	v_lshlrev_b32_e32 v2, 20, v4
	v_and_b32_e32 v47, 0xf00000, v2
	v_mul_f32_e32 v2, v12, v51
	v_rndne_f32_e32 v2, v2
	v_cvt_i32_f32_e32 v48, v2
	v_lshlrev_b64 v[2:3], 9, v[30:31]
	v_lshl_or_b32 v2, v10, 2, v2
	v_lshl_add_u64 v[6:7], s[20:21], 0, v[2:3]
	v_or_b32_e32 v4, 0x100, v2
	v_mov_b32_e32 v5, v3
	v_lshl_add_u64 v[34:35], s[20:21], 0, v[4:5]
	v_lshl_add_u64 v[36:37], s[24:25], 0, v[2:3]
	v_lshl_add_u64 v[38:39], s[24:25], 0, v[4:5]
	global_load_dword v2, v[6:7], off
	global_load_dword v3, v[34:35], off
	global_load_dword v4, v[36:37], off
	global_load_dword v5, v[38:39], off
	v_mul_f32_e32 v7, v12, v55
	v_rndne_f32_e32 v7, v7
	v_cvt_i32_f32_e32 v7, v7
	v_lshlrev_b32_e32 v34, 24, v48
	v_lshl_add_u32 v6, v48, 20, v126
	v_and_b32_e32 v35, 0xf000000, v34
	v_lshl_add_u32 v34, v7, 24, v127
	v_and_b32_e32 v6, 0xf000000, v6
	v_and_b32_e32 v34, 0xf0000000, v34
	v_or3_b32 v34, v46, v6, v34
	v_lshl_or_b32 v6, v7, 28, v27
	v_or3_b32 v6, v6, v42, v43
	v_or3_b32 v6, v6, v44, v45
	v_or3_b32 v35, v6, v47, v35
	v_mul_f32_e32 v6, v12, v56
	v_mul_f32_e32 v7, v12, v57
	v_rndne_f32_e32 v6, v6
	v_rndne_f32_e32 v7, v7
	v_cvt_i32_f32_e32 v6, v6
	v_cvt_i32_f32_e32 v7, v7
	v_mul_f32_e32 v37, v12, v58
	v_mul_f32_e32 v38, v12, v59
	v_rndne_f32_e32 v37, v37
	v_rndne_f32_e32 v38, v38
	v_cvt_i32_f32_e32 v37, v37
	v_cvt_i32_f32_e32 v38, v38
	v_add_u32_e32 v27, 8, v6
	v_add_u32_e32 v36, 8, v7
	v_lshrrev_b32_e32 v27, 4, v27
	v_and_b32_e32 v36, 0xf0, v36
	v_and_or_b32 v27, v27, 15, v36
	v_lshl_add_u32 v36, v37, 4, v122
	v_lshl_add_u32 v39, v38, 8, v123
	v_and_b32_e32 v36, 0xf00, v36
	v_and_b32_e32 v39, 0xf000, v39
	v_mul_f32_e32 v42, v12, v60
	v_or3_b32 v27, v27, v36, v39
	v_mul_f32_e32 v39, v12, v40
	v_rndne_f32_e32 v42, v42
	v_rndne_f32_e32 v39, v39
	v_cvt_i32_f32_e32 v42, v42
	v_cvt_i32_f32_e32 v39, v39
	v_mul_f32_e32 v43, v12, v61
	v_mul_f32_e32 v12, v12, v41
	v_rndne_f32_e32 v12, v12
	v_rndne_f32_e32 v43, v43
	v_cvt_i32_f32_e32 v12, v12
	v_lshlrev_b32_e32 v36, 12, v38
	v_cvt_i32_f32_e32 v43, v43
	v_and_b32_e32 v38, 0xf000, v36
	v_lshl_add_u32 v36, v42, 12, v124
	v_lshlrev_b32_e32 v40, 16, v42
	v_lshl_add_u32 v42, v39, 16, v125
	v_and_b32_e32 v6, 15, v6
	v_lshlrev_b32_e32 v7, 4, v7
	v_lshlrev_b32_e32 v37, 8, v37
	v_and_b32_e32 v36, 0xf0000, v36
	v_and_b32_e32 v42, 0xf00000, v42
	v_and_b32_e32 v7, 0xf0, v7
	v_and_b32_e32 v37, 0xf00, v37
	v_or3_b32 v27, v27, v36, v42
	v_lshlrev_b32_e32 v36, 20, v39
	v_lshl_or_b32 v6, v12, 28, v6
	v_and_b32_e32 v40, 0xf0000, v40
	v_and_b32_e32 v39, 0xf00000, v36
	v_lshl_add_u32 v36, v43, 20, v126
	v_lshlrev_b32_e32 v41, 24, v43
	v_lshl_add_u32 v42, v12, 24, v127
	v_or3_b32 v6, v6, v7, v37
	v_and_b32_e32 v36, 0xf000000, v36
	v_and_b32_e32 v41, 0xf000000, v41
	v_and_b32_e32 v42, 0xf0000000, v42
	v_or3_b32 v6, v6, v38, v40
	v_or3_b32 v36, v27, v36, v42
	v_or3_b32 v37, v6, v39, v41
	ds_write_b128 v128, v[34:37] offset:3584
	s_waitcnt vmcnt(3)
; __device__ __forceinline__ void p3_token(const Params& p, int tok, int lane, unsigned* rec, float& sh, int& hs8) {
;     ...
; #pragma unroll
;     for (int v = 0; v < 8; v++) {
;         const unsigned long long m0 = __ballot(k0 == v), m1 = __ballot(k1 == v);
;         const int c0 = __popcll(m0);
;         const int r0 = __builtin_amdgcn_mbcnt_hi((unsigned)(m0 >> 32), __builtin_amdgcn_mbcnt_lo((unsigned)m0, 0u));
;         const int r1 = __builtin_amdgcn_mbcnt_hi((unsigned)(m1 >> 32), __builtin_amdgcn_mbcnt_lo((unsigned)m1, 0u));
;         pos0 = (k0 == v) ? base + r0 : pos0;
;         pos1 = (k1 == v) ? base + c0 + r1 : pos1;
;         base += c0 + __popcll(m1);
;     }
;     const float* tsc = (const float*)(p.ws + OFF_UB + 33554432);
;     const f32x2 s0 = *(const f32x2*)(tsc + 2 * e0), s1 = *(const f32x2*)(tsc + 2 * e1);
;     rec[pos0] = (unsigned)e0; rec[pos1] = (unsigned)e1;
;     rec[128 + pos0] = __float_as_uint(g0 * s0[1]); rec[128 + pos1] = __float_as_uint(g1 * s1[1]);
;     rec[512 + pos0] = __float_as_uint(sh * s0[0]); rec[512 + pos1] = __float_as_uint(sh * s1[0]);
; }
	v_cmp_gt_u32_e32 vcc, s37, v2
	s_waitcnt vmcnt(2)
	v_cmp_gt_u32_e64 s[4:5], s37, v3
	s_bcnt1_i32_b64 s8, vcc
	s_and_saveexec_b64 s[6:7], s[4:5]
	v_mbcnt_lo_u32_b32 v0, s4, 0
	v_mbcnt_hi_u32_b32 v0, s5, v0
	v_add_u32_e32 v0, s8, v0
	s_or_b64 exec, exec, s[6:7]
	v_ashrrev_i32_e32 v6, 11, v2
	s_bcnt1_i32_b64 s42, s[4:5]
	v_cmp_eq_u32_e64 s[4:5], 1, v6
	v_ashrrev_i32_e32 v7, 11, v3
	s_add_i32 s42, s42, s8
	s_bcnt1_i32_b64 s8, s[4:5]
	v_cmp_eq_u32_e64 s[6:7], 1, v7
	s_add_i32 s43, s42, s8
	s_and_saveexec_b64 s[8:9], s[6:7]
	v_mbcnt_lo_u32_b32 v0, s6, 0
	v_mbcnt_hi_u32_b32 v0, s7, v0
	v_add_u32_e32 v0, s43, v0
	s_or_b64 exec, exec, s[8:9]
	s_bcnt1_i32_b64 s6, s[6:7]
	s_add_i32 s43, s43, s6
	v_cmp_eq_u32_e64 s[6:7], 2, v6
	s_bcnt1_i32_b64 s10, s[6:7]
	v_cmp_eq_u32_e64 s[8:9], 2, v7
	s_add_i32 s44, s43, s10
	s_and_saveexec_b64 s[10:11], s[8:9]
	v_mbcnt_lo_u32_b32 v0, s8, 0
	v_mbcnt_hi_u32_b32 v0, s9, v0
	v_add_u32_e32 v0, s44, v0
	s_or_b64 exec, exec, s[10:11]
	s_bcnt1_i32_b64 s8, s[8:9]
	s_add_i32 s44, s44, s8
	v_cmp_eq_u32_e64 s[8:9], 3, v6
	s_bcnt1_i32_b64 s12, s[8:9]
	v_cmp_eq_u32_e64 s[10:11], 3, v7
	s_add_i32 s45, s44, s12
	s_and_saveexec_b64 s[12:13], s[10:11]
	v_mbcnt_lo_u32_b32 v0, s10, 0
	v_mbcnt_hi_u32_b32 v0, s11, v0
	v_add_u32_e32 v0, s45, v0
	s_or_b64 exec, exec, s[12:13]
	s_bcnt1_i32_b64 s10, s[10:11]
	s_add_i32 s45, s45, s10
	v_cmp_eq_u32_e64 s[10:11], 4, v6
	s_bcnt1_i32_b64 s14, s[10:11]
	v_cmp_eq_u32_e64 s[12:13], 4, v7
	s_add_i32 s46, s45, s14
	s_and_saveexec_b64 s[14:15], s[12:13]
	v_mbcnt_lo_u32_b32 v0, s12, 0
	v_mbcnt_hi_u32_b32 v0, s13, v0
	v_add_u32_e32 v0, s46, v0
	s_or_b64 exec, exec, s[14:15]
	s_bcnt1_i32_b64 s12, s[12:13]
	s_add_i32 s46, s46, s12
	v_cmp_eq_u32_e64 s[12:13], 5, v6
	s_bcnt1_i32_b64 s16, s[12:13]
	v_cmp_eq_u32_e64 s[14:15], 5, v7
	s_add_i32 s47, s46, s16
	s_and_saveexec_b64 s[16:17], s[14:15]
	v_mbcnt_lo_u32_b32 v0, s14, 0
	v_mbcnt_hi_u32_b32 v0, s15, v0
	v_add_u32_e32 v0, s47, v0
	s_or_b64 exec, exec, s[16:17]
	s_bcnt1_i32_b64 s14, s[14:15]
	s_add_i32 s47, s47, s14
	v_cmp_eq_u32_e64 s[14:15], 6, v6
	s_bcnt1_i32_b64 s18, s[14:15]
	v_cmp_eq_u32_e64 s[16:17], 6, v7
	s_add_i32 s48, s47, s18
	s_and_saveexec_b64 s[18:19], s[16:17]
	v_mbcnt_lo_u32_b32 v0, s16, 0
	v_mbcnt_hi_u32_b32 v0, s17, v0
	v_add_u32_e32 v0, s48, v0
	s_or_b64 exec, exec, s[18:19]
	s_bcnt1_i32_b64 s16, s[16:17]
	s_add_i32 s48, s48, s16
	v_cmp_eq_u32_e64 s[16:17], 7, v6
	v_cmp_eq_u32_e64 s[18:19], 7, v7
	s_and_saveexec_b64 s[34:35], s[18:19]
	s_bcnt1_i32_b64 s49, s[16:17]
	v_mbcnt_lo_u32_b32 v0, s18, 0
	s_add_i32 s49, s48, s49
	v_mbcnt_hi_u32_b32 v0, s19, v0
	v_add_u32_e32 v0, s49, v0
	s_or_b64 exec, exec, s[34:35]
	v_lshlrev_b32_e32 v6, 1, v2
	v_ashrrev_i32_e32 v7, 31, v6
	v_lshlrev_b32_e32 v34, 1, v3
	v_lshl_add_u64 v[6:7], v[6:7], 2, s[26:27]
	v_ashrrev_i32_e32 v35, 31, v34
	v_lshl_add_u64 v[34:35], v[34:35], 2, s[26:27]
	global_load_dwordx2 v[36:37], v[6:7], off
	global_load_dwordx2 v[38:39], v[34:35], off
	v_mbcnt_lo_u32_b32 v41, s4, 0
	v_mbcnt_lo_u32_b32 v42, vcc_lo, 0
	v_mbcnt_lo_u32_b32 v40, s6, 0
	v_mbcnt_hi_u32_b32 v41, s5, v41
	v_mbcnt_hi_u32_b32 v42, vcc_hi, v42
	v_mbcnt_lo_u32_b32 v34, s8, 0
	v_mbcnt_hi_u32_b32 v40, s7, v40
	v_add_u32_e32 v41, s42, v41
	v_cndmask_b32_e32 v42, 0, v42, vcc
	v_mbcnt_lo_u32_b32 v27, s10, 0
	v_mbcnt_hi_u32_b32 v34, s9, v34
	v_add_u32_e32 v40, s43, v40
	v_cndmask_b32_e64 v41, v42, v41, s[4:5]
	v_mbcnt_lo_u32_b32 v12, s12, 0
	v_mbcnt_hi_u32_b32 v27, s11, v27
	v_add_u32_e32 v34, s44, v34
	v_cndmask_b32_e64 v40, v41, v40, s[6:7]
	v_mbcnt_lo_u32_b32 v7, s14, 0
	v_mbcnt_hi_u32_b32 v12, s13, v12
	v_add_u32_e32 v27, s45, v27
	v_cndmask_b32_e64 v34, v40, v34, s[8:9]
	v_mbcnt_lo_u32_b32 v6, s16, 0
	v_mbcnt_hi_u32_b32 v7, s15, v7
	v_add_u32_e32 v12, s46, v12
	v_cndmask_b32_e64 v27, v34, v27, s[10:11]
	v_mbcnt_hi_u32_b32 v6, s17, v6
	v_add_u32_e32 v7, s47, v7
	v_cndmask_b32_e64 v12, v27, v12, s[12:13]
	v_add_u32_e32 v6, s48, v6
	v_cndmask_b32_e64 v7, v12, v7, s[14:15]
	v_cndmask_b32_e64 v6, v7, v6, s[16:17]
	v_mul_f32_e32 v1, 0x3c09ae41, v1
	v_lshl_add_u32 v6, v6, 2, v11
	v_lshl_add_u32 v0, v0, 2, v11
	ds_write_b32 v6, v2 offset:2560
	ds_write_b32 v0, v3 offset:2560
	v_mov_b32_e32 v35, v13
	v_mov_b32_e32 v41, v13
	s_mov_b32 s5, 0
	s_waitcnt vmcnt(1)
	v_mul_f32_e32 v2, v4, v37
	s_waitcnt vmcnt(0)
	v_mul_f32_e32 v3, v5, v39
	v_mul_f32_e32 v4, v1, v36
	v_mul_f32_e32 v1, v1, v38
	ds_write_b32 v6, v2 offset:3072
	ds_write_b32 v0, v3 offset:3072
	ds_write_b32 v6, v4 offset:4608
	ds_write_b32 v0, v1 offset:4608
	ds_read_b128 v[0:3], v11
	ds_read_b128 v[4:7], v11 offset:2560
	v_mov_b32_e32 v37, v13
	v_mov_b32_e32 v39, v13
	s_waitcnt lgkmcnt(1)
	v_mov_b32_e32 v12, v0
	v_mov_b32_e32 v34, v1
	v_mov_b32_e32 v36, v3
	s_waitcnt lgkmcnt(0)
; __device__ __forceinline__ void p3_load_u(u32x2 (&ur)[4], P3Sc& sc, const unsigned char* __restrict__ UQ, const float* __restrict__ tsc,
;                                           int lane, int ul, int g, const unsigned* rec) {
; #pragma unroll
;     for (int u = 0; u < 4; u++) ur[u] = *(const u32x2*)(UQ + (size_t)rec[4 * g + u] * 512 + lane * 8);
;     sc.gm = __uint_as_float(rec[128 + 4 * g + ul]);
;     sc.su = __uint_as_float(rec[512 + 4 * g + ul]);
;     sc.sv = 1.f;
; }
; __device__ __forceinline__ void p3_load_v(u32x2 (&vr)[4], const unsigned char* __restrict__ VQ, int lane, int g, const unsigned* rec) {
; #pragma unroll
;     for (int u = 0; u < 4; u++) vr[u] = *(const u32x2*)(VQ + (size_t)rec[4 * g + u] * 512 + lane * 8);
; }
; __device__ __forceinline__ void p3_dots(const u32x2 (&ur)[4], const unsigned* rec, int lane, int (&pt)[4]) {
;     const u32x4 qh = *(const u32x4*)(rec + 256 + lane * 4);
; #pragma unroll
;     for (int u = 0; u < 4; u++) {
;         const int w0 = (int)ur[u].x, w1 = (int)ur[u].y;
;         int dh = __builtin_amdgcn_sdot8(w0, (int)qh.x, 0, false);
;         dh = __builtin_amdgcn_sdot8(w1, (int)qh.z, dh, false);
;         int dl = __builtin_amdgcn_sdot8(w0, (int)qh.y, 0, false);
;         dl = __builtin_amdgcn_sdot8(w1, (int)qh.w, dl, false);
;         pt[u] = (dh << 4) + dl;
;     }
; }
; __device__ void phaseP3(const Params& p, float* dstp, char* lds) {
;     ...
; #pragma unroll
;         for (int k = 0; k < TPW; k++) {
;             p3_load_u(ur[k], sc[k], UQ, tsc, lane, ul, 0, recs + k * (P3_REC / 4));
;             p3_load_v(vr[k], VQ, lane, 0, recs + k * (P3_REC / 4));
;         }
;         for (int g = 0; g < 32; g++) {
; #pragma unroll
;             for (int k = 0; k < TPW; k++) {
;                 int pt[4];
;                 p3_dots(ur[k], recs + k * (P3_REC / 4), lane, pt);
;                 const P3Sc sck = sc[k];
;                 if (g + 1 < 32) p3_load_u(ur[k], sc[k], UQ, tsc, lane, ul, g + 1, recs + k * (P3_REC / 4));
	v_mov_b32_e32 v38, v5
	v_mov_b32_e32 v40, v7
	v_lshlrev_b64 v[0:1], 9, v[34:35]
	v_lshlrev_b64 v[34:35], 9, v[12:13]
	v_mov_b32_e32 v12, v2
	v_lshlrev_b64 v[2:3], 9, v[36:37]
	v_lshlrev_b64 v[36:37], 9, v[38:39]
	v_lshlrev_b64 v[38:39], 9, v[40:41]
	v_lshl_add_u64 v[40:41], v[14:15], 0, v[34:35]
	v_lshlrev_b64 v[44:45], 9, v[12:13]
	v_lshl_add_u64 v[42:43], v[14:15], 0, v[0:1]
	v_lshl_add_u64 v[46:47], v[14:15], 0, v[2:3]
	v_lshl_add_u64 v[34:35], v[16:17], 0, v[34:35]
	v_lshl_add_u64 v[0:1], v[16:17], 0, v[0:1]
	v_lshl_add_u64 v[2:3], v[16:17], 0, v[2:3]
	v_mov_b32_e32 v12, v4
	v_lshl_add_u64 v[50:51], v[14:15], 0, v[44:45]
	v_lshl_add_u64 v[44:45], v[16:17], 0, v[44:45]
	global_load_dwordx2 v[80:81], v[40:41], off
	global_load_dwordx2 v[74:75], v[42:43], off
	global_load_dwordx2 v[84:85], v[50:51], off
	global_load_dwordx2 v[82:83], v[46:47], off
	global_load_dwordx2 v[72:73], v[34:35], off
	global_load_dwordx2 v[70:71], v[0:1], off
	global_load_dwordx2 v[62:63], v[44:45], off
	global_load_dwordx2 v[58:59], v[2:3], off
	v_lshlrev_b64 v[52:53], 9, v[12:13]
	v_mov_b32_e32 v12, v6
	v_lshl_add_u64 v[0:1], v[14:15], 0, v[52:53]
	v_lshlrev_b64 v[2:3], 9, v[12:13]
	v_lshl_add_u64 v[4:5], v[14:15], 0, v[36:37]
	v_lshl_add_u64 v[48:49], v[14:15], 0, v[38:39]
	v_lshl_add_u64 v[6:7], v[14:15], 0, v[2:3]
	global_load_dwordx2 v[66:67], v[0:1], off
	global_load_dwordx2 v[60:61], v[4:5], off
	global_load_dwordx2 v[68:69], v[6:7], off
	global_load_dwordx2 v[64:65], v[48:49], off
	v_lshl_add_u64 v[0:1], v[16:17], 0, v[52:53]
	v_lshl_add_u64 v[4:5], v[16:17], 0, v[36:37]
	v_lshl_add_u64 v[2:3], v[16:17], 0, v[2:3]
	v_lshl_add_u64 v[6:7], v[16:17], 0, v[38:39]
	global_load_dwordx2 v[40:41], v[0:1], off
	global_load_dwordx2 v[38:39], v[4:5], off
	global_load_dwordx2 v[36:37], v[2:3], off
	global_load_dwordx2 v[34:35], v[6:7], off
	ds_read2st64_b32 v[76:77], v119 offset0:2 offset1:8
	ds_read2st64_b32 v[78:79], v119 offset0:12 offset1:18
	ds_read_b128 v[4:7], v128 offset:1024
	ds_read_b128 v[0:3], v128 offset:3584
	v_mov_b32_e32 v42, 0
	v_mov_b32_e32 v43, v42
	v_mov_b32_e32 v44, v42
	v_mov_b32_e32 v45, v42
	v_mov_b32_e32 v46, v42
	v_mov_b32_e32 v47, v42
	v_mov_b32_e32 v48, v42
	v_mov_b32_e32 v49, v42
	v_mov_b32_e32 v50, v42
	v_mov_b32_e32 v51, v42
	v_mov_b32_e32 v52, v42
	v_mov_b32_e32 v53, v42
	v_mov_b32_e32 v86, v42
	v_mov_b32_e32 v87, v42
	v_mov_b32_e32 v88, v42
	v_mov_b32_e32 v89, v42
	v_mov_b32_e32 v90, v42
	v_mov_b32_e32 v91, v42
	v_mov_b32_e32 v92, v42
	v_mov_b32_e32 v93, v42
	v_mov_b32_e32 v94, v42
	v_mov_b32_e32 v95, v42
	v_mov_b32_e32 v96, v42
	v_mov_b32_e32 v97, v42
	v_mov_b32_e32 v98, v42
	v_mov_b32_e32 v99, v42
	v_mov_b32_e32 v100, v42
	v_mov_b32_e32 v101, v42
	v_mov_b32_e32 v54, v42
	v_mov_b32_e32 v55, v42
	v_mov_b32_e32 v56, v42
	v_mov_b32_e32 v57, v42
	ds_read_b128 v[200:203], v121
	ds_read_b128 v[204:207], v121 offset:2560
	s_waitcnt lgkmcnt(0)
	v_lshl_add_u32 v200, v200, 9, v136
	v_lshl_add_u32 v201, v201, 9, v136
	v_lshl_add_u32 v202, v202, 9, v136
	v_lshl_add_u32 v203, v203, 9, v136
	v_lshl_add_u32 v204, v204, 9, v136
	v_lshl_add_u32 v205, v205, 9, v136
	v_lshl_add_u32 v206, v206, 9, v136
	v_lshl_add_u32 v207, v207, 9, v136
	global_load_dwordx2 v[184:185], v200, s[50:51]
	global_load_dwordx2 v[186:187], v201, s[50:51]
	global_load_dwordx2 v[188:189], v202, s[50:51]
	global_load_dwordx2 v[190:191], v203, s[50:51]
	global_load_dwordx2 v[192:193], v204, s[50:51]
	global_load_dwordx2 v[194:195], v205, s[50:51]
	global_load_dwordx2 v[196:197], v206, s[50:51]
	global_load_dwordx2 v[198:199], v207, s[50:51]
	s_waitcnt lgkmcnt(0)
	v_cndmask_b32_e64 v76, v76, v78, s[54:55]
	v_cndmask_b32_e64 v77, v77, v79, s[54:55]
	.p2alignl 6, 3212836864
.LBB0_1075:
	v_add_u32_e32 v134, s5, v121
	v_add_u32_e32 v135, s5, v137
	ds_read_b128 v[140:143], v134
	ds_read_b128 v[144:147], v134 offset:2560
	ds_read_b128 v[200:203], v134 offset:16
	ds_read_b128 v[204:207], v134 offset:2576
	s_waitcnt vmcnt(16) lgkmcnt(4)
	v_dot8_i32_i4 v12, v80, v4, 0
	v_dot8_i32_i4 v27, v80, v5, 0
	v_dot8_i32_i4 v131, v74, v4, 0
	v_dot8_i32_i4 v132, v74, v5, 0
	v_dot8c_i32_i4_e32 v12, v81, v6
	v_dot8c_i32_i4_e32 v27, v81, v7
	v_dot8c_i32_i4_e32 v131, v75, v6
	v_dot8c_i32_i4_e32 v132, v75, v7
	v_dot8_i32_i4 v133, v84, v4, 0
	v_dot8_i32_i4 v176, v84, v5, 0
	v_dot8_i32_i4 v177, v82, v4, 0
	v_dot8_i32_i4 v178, v82, v5, 0
	v_dot8c_i32_i4_e32 v133, v85, v6
	v_dot8c_i32_i4_e32 v176, v85, v7
	v_dot8c_i32_i4_e32 v177, v83, v6
	v_dot8c_i32_i4_e32 v178, v83, v7
	v_lshl_add_u32 v27, v12, 4, v27
	v_lshl_add_u32 v131, v131, 4, v132
	v_lshl_add_u32 v132, v133, 4, v176
	v_lshl_add_u32 v133, v177, 4, v178
	v_cndmask_b32_e64 v12, v132, v27, s[0:1]
	v_cndmask_b32_e64 v27, v27, v132, s[0:1]
	s_waitcnt lgkmcnt(0)
	v_lshl_add_u32 v200, v200, 9, v136
	v_add_u32_dpp v12, v27, v12 quad_perm:[1,0,3,2] row_mask:0xf bank_mask:0xf bound_ctrl:1
	v_cndmask_b32_e64 v27, v133, v131, s[0:1]
	v_cndmask_b32_e64 v131, v131, v133, s[0:1]
	v_lshl_add_u32 v201, v201, 9, v136
	v_lshl_add_u32 v202, v202, 9, v136
	v_add_u32_dpp v27, v131, v27 quad_perm:[1,0,3,2] row_mask:0xf bank_mask:0xf bound_ctrl:1
	v_cndmask_b32_e64 v131, v27, v12, s[2:3]
	v_cndmask_b32_e64 v12, v12, v27, s[2:3]
	v_lshl_add_u32 v203, v203, 9, v136
	global_load_dwordx2 v[80:81], v200, s[50:51]
	v_add_u32_dpp v12, v12, v131 quad_perm:[2,3,0,1] row_mask:0xf bank_mask:0xf bound_ctrl:1
	global_load_dwordx2 v[74:75], v201, s[50:51]
	global_load_dwordx2 v[84:85], v202, s[50:51]
	v_add_u32_dpp v12, v12, v12 row_ror:4 row_mask:0xf bank_mask:0xf bound_ctrl:1
	global_load_dwordx2 v[82:83], v203, s[50:51]
	s_waitcnt vmcnt(8)
; __device__ __forceinline__ void p3_dots(const u32x2 (&ur)[4], const unsigned* rec, int lane, int (&pt)[4]) {
;     const u32x4 qh = *(const u32x4*)(rec + 256 + lane * 4);
; #pragma unroll
;     for (int u = 0; u < 4; u++) {
;         const int w0 = (int)ur[u].x, w1 = (int)ur[u].y;
;         int dh = __builtin_amdgcn_sdot8(w0, (int)qh.x, 0, false);
;         dh = __builtin_amdgcn_sdot8(w1, (int)qh.z, dh, false);
;         int dl = __builtin_amdgcn_sdot8(w0, (int)qh.y, 0, false);
;         dl = __builtin_amdgcn_sdot8(w1, (int)qh.w, dl, false);
;         pt[u] = (dh << 4) + dl;
;     }
; }
; template <int CTRL> __device__ __forceinline__ int dpp_i(int v) { return __builtin_amdgcn_mov_dpp(v, CTRL, 0xF, 0xF, true); }
; __device__ __forceinline__ int xrow_sum_i(int v) {
;     const auto a = __builtin_amdgcn_permlane16_swap((unsigned)v, (unsigned)v, false, false);
;     v = (int)a[0] + (int)a[1];
;     const auto b = __builtin_amdgcn_permlane32_swap((unsigned)v, (unsigned)v, false, false);
;     return (int)b[0] + (int)b[1];
; }
; __device__ __forceinline__ float p3_weight(const int (&pt)[4], int lane, float sh, int hs8, const P3Sc& sc) {
;     int m2[2], m1;
;     const bool c0 = lane & 1;
; #pragma unroll
;     for (int j = 0; j < 2; j++) { const int keep = c0 ? pt[j + 2] : pt[j], send = c0 ? pt[j] : pt[j + 2]; m2[j] = keep + dpp_i<0xB1>(send); }
;     const bool c1 = lane & 2;
;     { const int keep = c1 ? m2[1] : m2[0], send = c1 ? m2[0] : m2[1]; m1 = keep + dpp_i<0x4E>(send); }
;     m1 += dpp_i<0x124>(m1);
;     m1 += dpp_i<0x128>(m1);
;     m1 = xrow_sum_i(m1);
;     const float aval = (float)(m1 - hs8) * sc.su;
;     return sc.gm * gelu_erf(aval);
; }
; __device__ __forceinline__ void p3_axpy(const u32x2 (&vr)[4], float ws, f32x2 (&acc)[8]) {
; #pragma unroll
;     for (int u = 0; u < 4; u++) {
;         const int la = ((u >> 1) & 1) | ((u & 1) << 1);
;         const float wu = __builtin_bit_cast(float, __builtin_amdgcn_readlane(__builtin_bit_cast(int, ws), la));
;         const f32x2 w2 = {wu, wu};
;         const unsigned vw[2] = {vr[u].x, vr[u].y};
; #pragma unroll
;         for (int i = 0; i < 2; i++) {
;             acc[i * 4 + 0] = __builtin_elementwise_fma(w2, __builtin_amdgcn_cvt_scalef32_pk_f32_fp4(vw[i], 1.0f, 0), acc[i * 4 + 0]);
	v_add_u32_dpp v181, v12, v12 row_ror:8 row_mask:0xf bank_mask:0xf bound_ctrl:1
	v_lshl_add_u32 v140, v140, 9, v136
	v_lshl_add_u32 v141, v141, 9, v136
	v_lshl_add_u32 v142, v142, 9, v136
	v_lshl_add_u32 v143, v143, 9, v136
	v_dot8_i32_i4 v12, v66, v0, 0
	v_dot8_i32_i4 v27, v66, v1, 0
	v_dot8_i32_i4 v131, v60, v0, 0
	v_dot8_i32_i4 v132, v60, v1, 0
	v_dot8c_i32_i4_e32 v12, v67, v2
	v_dot8c_i32_i4_e32 v27, v67, v3
	v_dot8c_i32_i4_e32 v131, v61, v2
	v_dot8c_i32_i4_e32 v132, v61, v3
	v_dot8_i32_i4 v133, v68, v0, 0
	v_dot8_i32_i4 v176, v68, v1, 0
	v_dot8_i32_i4 v177, v64, v0, 0
	v_dot8_i32_i4 v178, v64, v1, 0
	v_dot8c_i32_i4_e32 v133, v69, v2
	v_dot8c_i32_i4_e32 v176, v69, v3
	v_dot8c_i32_i4_e32 v177, v65, v2
	v_dot8c_i32_i4_e32 v178, v65, v3
	v_lshl_add_u32 v27, v12, 4, v27
	v_lshl_add_u32 v131, v131, 4, v132
	v_lshl_add_u32 v132, v133, 4, v176
	v_lshl_add_u32 v133, v177, 4, v178
	v_cndmask_b32_e64 v12, v132, v27, s[0:1]
	v_cndmask_b32_e64 v27, v27, v132, s[0:1]
	v_lshl_add_u32 v204, v204, 9, v136
	v_lshl_add_u32 v205, v205, 9, v136
	v_add_u32_dpp v12, v27, v12 quad_perm:[1,0,3,2] row_mask:0xf bank_mask:0xf bound_ctrl:1
	v_cndmask_b32_e64 v27, v133, v131, s[0:1]
	v_cndmask_b32_e64 v131, v131, v133, s[0:1]
	v_lshl_add_u32 v206, v206, 9, v136
	v_lshl_add_u32 v207, v207, 9, v136
	v_add_u32_dpp v27, v131, v27 quad_perm:[1,0,3,2] row_mask:0xf bank_mask:0xf bound_ctrl:1
	v_cndmask_b32_e64 v131, v27, v12, s[2:3]
	v_cndmask_b32_e64 v12, v12, v27, s[2:3]
	global_load_dwordx2 v[66:67], v204, s[50:51]
	global_load_dwordx2 v[60:61], v205, s[50:51]
	v_add_u32_dpp v12, v12, v131 quad_perm:[2,3,0,1] row_mask:0xf bank_mask:0xf bound_ctrl:1
	global_load_dwordx2 v[68:69], v206, s[50:51]
	global_load_dwordx2 v[64:65], v207, s[50:51]
	v_add_u32_dpp v12, v12, v12 row_ror:4 row_mask:0xf bank_mask:0xf bound_ctrl:1
	v_cvt_scalef32_pk_f32_fp4 v[160:161], v72, 1.0
	v_cvt_scalef32_pk_f32_fp4 v[162:163], v72, 1.0 op_sel:[1,0,0]
	v_add_u32_dpp v12, v12, v12 row_ror:8 row_mask:0xf bank_mask:0xf bound_ctrl:1
	v_lshl_add_u32 v144, v144, 9, v136
	v_lshl_add_u32 v145, v145, 9, v136
	v_lshl_add_u32 v146, v146, 9, v136
	v_lshl_add_u32 v147, v147, 9, v136
	v_cvt_scalef32_pk_f32_fp4 v[164:165], v72, 1.0 op_sel:[0,1,0]
	v_cvt_scalef32_pk_f32_fp4 v[166:167], v72, 1.0 op_sel:[1,1,0]
	v_permlane16_swap_b32_e32 v181, v12
	v_add_u32_e32 v12, v181, v12
	v_mov_b32_e32 v27, v12
	v_cvt_scalef32_pk_f32_fp4 v[168:169], v73, 1.0
	v_cvt_scalef32_pk_f32_fp4 v[170:171], v73, 1.0 op_sel:[1,0,0]
	v_permlane32_swap_b32_e32 v12, v27
	v_add_u32_e32 v12, v27, v12
	v_cvt_f32_i32_e32 v12, v12
	v_mul_f32_e32 v12, v77, v12
	v_fma_f32 v179, |v12|, s39, 1.0
	v_rcp_f32_e32 v179, v179
	v_cmp_gt_f32_e32 vcc, 0, v12
	v_fmamk_f32 v180, v179, 0x3f07dc22, v129
	v_fmaak_f32 v180, v179, v180, 0x3f35f0e3
	v_fmaak_f32 v180, v179, v180, 0xbe11a98e
	v_fmaak_f32 v180, v179, v180, 0x3e027906
	v_mul_f32_e32 v179, v179, v180
	v_mul_f32_e32 v180, v12, v12
	v_mul_f32_e32 v180, 0xbf38aa3b, v180
	v_exp_f32_e32 v180, v180
	v_cvt_scalef32_pk_f32_fp4 v[172:173], v73, 1.0 op_sel:[0,1,0]
	v_mul_f32_e32 v179, v180, v179
	v_mul_f32_e32 v180, v12, v179
	v_fma_f32 v12, -v12, v179, v12
	v_cndmask_b32_e32 v12, v12, v180, vcc
	v_mul_f32_e32 v12, v76, v12
	ds_read2st64_b32 v[76:77], v135 offset1:6
	v_readlane_b32 s4, v12, 0
	v_cvt_scalef32_pk_f32_fp4 v[174:175], v73, 1.0 op_sel:[1,1,0]
	global_load_dwordx2 v[72:73], v140, s[52:53]
	v_pk_fma_f32 v[100:101], s[4:5], v[160:161], v[100:101] op_sel_hi:[0,1,1]
	v_pk_fma_f32 v[98:99], s[4:5], v[162:163], v[98:99] op_sel_hi:[0,1,1]
	v_pk_fma_f32 v[96:97], s[4:5], v[164:165], v[96:97] op_sel_hi:[0,1,1]
	v_pk_fma_f32 v[94:95], s[4:5], v[166:167], v[94:95] op_sel_hi:[0,1,1]
	v_pk_fma_f32 v[92:93], s[4:5], v[168:169], v[92:93] op_sel_hi:[0,1,1]
	v_pk_fma_f32 v[90:91], s[4:5], v[170:171], v[90:91] op_sel_hi:[0,1,1]
	v_pk_fma_f32 v[88:89], s[4:5], v[172:173], v[88:89] op_sel_hi:[0,1,1]
	v_pk_fma_f32 v[86:87], s[4:5], v[174:175], v[86:87] op_sel_hi:[0,1,1]
	v_readlane_b32 s4, v12, 2
	v_cvt_scalef32_pk_f32_fp4 v[160:161], v70, 1.0
	v_cvt_scalef32_pk_f32_fp4 v[162:163], v70, 1.0 op_sel:[1,0,0]
	v_pk_fma_f32 v[100:101], s[4:5], v[160:161], v[100:101] op_sel_hi:[0,1,1]
	v_cvt_scalef32_pk_f32_fp4 v[164:165], v70, 1.0 op_sel:[0,1,0]
	v_pk_fma_f32 v[98:99], s[4:5], v[162:163], v[98:99] op_sel_hi:[0,1,1]
	v_cvt_scalef32_pk_f32_fp4 v[166:167], v70, 1.0 op_sel:[1,1,0]
	v_pk_fma_f32 v[96:97], s[4:5], v[164:165], v[96:97] op_sel_hi:[0,1,1]
	v_cvt_scalef32_pk_f32_fp4 v[168:169], v71, 1.0
	v_pk_fma_f32 v[94:95], s[4:5], v[166:167], v[94:95] op_sel_hi:[0,1,1]
	v_cvt_scalef32_pk_f32_fp4 v[170:171], v71, 1.0 op_sel:[1,0,0]
	v_pk_fma_f32 v[92:93], s[4:5], v[168:169], v[92:93] op_sel_hi:[0,1,1]
	v_cvt_scalef32_pk_f32_fp4 v[172:173], v71, 1.0 op_sel:[0,1,0]
	v_pk_fma_f32 v[90:91], s[4:5], v[170:171], v[90:91] op_sel_hi:[0,1,1]
	v_cvt_scalef32_pk_f32_fp4 v[174:175], v71, 1.0 op_sel:[1,1,0]
	v_pk_fma_f32 v[88:89], s[4:5], v[172:173], v[88:89] op_sel_hi:[0,1,1]
	v_pk_fma_f32 v[86:87], s[4:5], v[174:175], v[86:87] op_sel_hi:[0,1,1]
	global_load_dwordx2 v[70:71], v141, s[52:53]
	v_readlane_b32 s4, v12, 1
	v_cvt_scalef32_pk_f32_fp4 v[160:161], v62, 1.0
	v_cvt_scalef32_pk_f32_fp4 v[162:163], v62, 1.0 op_sel:[1,0,0]
	v_pk_fma_f32 v[100:101], s[4:5], v[160:161], v[100:101] op_sel_hi:[0,1,1]
	v_cvt_scalef32_pk_f32_fp4 v[164:165], v62, 1.0 op_sel:[0,1,0]
	v_pk_fma_f32 v[98:99], s[4:5], v[162:163], v[98:99] op_sel_hi:[0,1,1]
	v_cvt_scalef32_pk_f32_fp4 v[166:167], v62, 1.0 op_sel:[1,1,0]
	v_pk_fma_f32 v[96:97], s[4:5], v[164:165], v[96:97] op_sel_hi:[0,1,1]
	v_cvt_scalef32_pk_f32_fp4 v[168:169], v63, 1.0
; __device__ __forceinline__ void p3_load_v(u32x2 (&vr)[4], const unsigned char* __restrict__ VQ, int lane, int g, const unsigned* rec) {
; #pragma unroll
;     for (int u = 0; u < 4; u++) vr[u] = *(const u32x2*)(VQ + (size_t)rec[4 * g + u] * 512 + lane * 8);
; }
; __device__ __forceinline__ void p3_axpy(const u32x2 (&vr)[4], float ws, f32x2 (&acc)[8]) {
; #pragma unroll
;     for (int u = 0; u < 4; u++) {
;         const int la = ((u >> 1) & 1) | ((u & 1) << 1);
;         const float wu = __builtin_bit_cast(float, __builtin_amdgcn_readlane(__builtin_bit_cast(int, ws), la));
;         const f32x2 w2 = {wu, wu};
;         const unsigned vw[2] = {vr[u].x, vr[u].y};
; #pragma unroll
;         for (int i = 0; i < 2; i++) {
;             acc[i * 4 + 0] = __builtin_elementwise_fma(w2, __builtin_amdgcn_cvt_scalef32_pk_f32_fp4(vw[i], 1.0f, 0), acc[i * 4 + 0]);
;             acc[i * 4 + 1] = __builtin_elementwise_fma(w2, __builtin_amdgcn_cvt_scalef32_pk_f32_fp4(vw[i], 1.0f, 1), acc[i * 4 + 1]);
;             acc[i * 4 + 2] = __builtin_elementwise_fma(w2, __builtin_amdgcn_cvt_scalef32_pk_f32_fp4(vw[i], 1.0f, 2), acc[i * 4 + 2]);
;             acc[i * 4 + 3] = __builtin_elementwise_fma(w2, __builtin_amdgcn_cvt_scalef32_pk_f32_fp4(vw[i], 1.0f, 3), acc[i * 4 + 3]);
;         }
;     }
; }
	v_pk_fma_f32 v[94:95], s[4:5], v[166:167], v[94:95] op_sel_hi:[0,1,1]
	v_cvt_scalef32_pk_f32_fp4 v[170:171], v63, 1.0 op_sel:[1,0,0]
	v_pk_fma_f32 v[92:93], s[4:5], v[168:169], v[92:93] op_sel_hi:[0,1,1]
	v_cvt_scalef32_pk_f32_fp4 v[172:173], v63, 1.0 op_sel:[0,1,0]
	v_pk_fma_f32 v[90:91], s[4:5], v[170:171], v[90:91] op_sel_hi:[0,1,1]
	v_cvt_scalef32_pk_f32_fp4 v[174:175], v63, 1.0 op_sel:[1,1,0]
	v_pk_fma_f32 v[88:89], s[4:5], v[172:173], v[88:89] op_sel_hi:[0,1,1]
	v_pk_fma_f32 v[86:87], s[4:5], v[174:175], v[86:87] op_sel_hi:[0,1,1]
	global_load_dwordx2 v[62:63], v142, s[52:53]
	v_readlane_b32 s4, v12, 3
	v_cvt_scalef32_pk_f32_fp4 v[160:161], v58, 1.0
	v_cvt_scalef32_pk_f32_fp4 v[162:163], v58, 1.0 op_sel:[1,0,0]
	v_pk_fma_f32 v[100:101], s[4:5], v[160:161], v[100:101] op_sel_hi:[0,1,1]
	v_cvt_scalef32_pk_f32_fp4 v[164:165], v58, 1.0 op_sel:[0,1,0]
	v_pk_fma_f32 v[98:99], s[4:5], v[162:163], v[98:99] op_sel_hi:[0,1,1]
	v_cvt_scalef32_pk_f32_fp4 v[166:167], v58, 1.0 op_sel:[1,1,0]
	v_pk_fma_f32 v[96:97], s[4:5], v[164:165], v[96:97] op_sel_hi:[0,1,1]
	v_cvt_scalef32_pk_f32_fp4 v[168:169], v59, 1.0
	v_pk_fma_f32 v[94:95], s[4:5], v[166:167], v[94:95] op_sel_hi:[0,1,1]
	v_cvt_scalef32_pk_f32_fp4 v[170:171], v59, 1.0 op_sel:[1,0,0]
	v_pk_fma_f32 v[92:93], s[4:5], v[168:169], v[92:93] op_sel_hi:[0,1,1]
	v_cvt_scalef32_pk_f32_fp4 v[172:173], v59, 1.0 op_sel:[0,1,0]
	v_pk_fma_f32 v[90:91], s[4:5], v[170:171], v[90:91] op_sel_hi:[0,1,1]
	v_cvt_scalef32_pk_f32_fp4 v[174:175], v59, 1.0 op_sel:[1,1,0]
	v_pk_fma_f32 v[88:89], s[4:5], v[172:173], v[88:89] op_sel_hi:[0,1,1]
	v_pk_fma_f32 v[86:87], s[4:5], v[174:175], v[86:87] op_sel_hi:[0,1,1]
	global_load_dwordx2 v[58:59], v143, s[52:53]
	s_waitcnt vmcnt(15)
	v_readlane_b32 s4, v12, 16
	v_cvt_scalef32_pk_f32_fp4 v[160:161], v40, 1.0
	v_cvt_scalef32_pk_f32_fp4 v[162:163], v40, 1.0 op_sel:[1,0,0]
	v_pk_fma_f32 v[52:53], s[4:5], v[160:161], v[52:53] op_sel_hi:[0,1,1]
	v_cvt_scalef32_pk_f32_fp4 v[164:165], v40, 1.0 op_sel:[0,1,0]
	v_pk_fma_f32 v[50:51], s[4:5], v[162:163], v[50:51] op_sel_hi:[0,1,1]
	v_cvt_scalef32_pk_f32_fp4 v[166:167], v40, 1.0 op_sel:[1,1,0]
	v_pk_fma_f32 v[48:49], s[4:5], v[164:165], v[48:49] op_sel_hi:[0,1,1]
	v_cvt_scalef32_pk_f32_fp4 v[168:169], v41, 1.0
	v_pk_fma_f32 v[46:47], s[4:5], v[166:167], v[46:47] op_sel_hi:[0,1,1]
	v_cvt_scalef32_pk_f32_fp4 v[170:171], v41, 1.0 op_sel:[1,0,0]
	v_pk_fma_f32 v[44:45], s[4:5], v[168:169], v[44:45] op_sel_hi:[0,1,1]
	v_cvt_scalef32_pk_f32_fp4 v[172:173], v41, 1.0 op_sel:[0,1,0]
	v_pk_fma_f32 v[42:43], s[4:5], v[170:171], v[42:43] op_sel_hi:[0,1,1]
	v_cvt_scalef32_pk_f32_fp4 v[174:175], v41, 1.0 op_sel:[1,1,0]
	v_pk_fma_f32 v[54:55], s[4:5], v[172:173], v[54:55] op_sel_hi:[0,1,1]
	v_pk_fma_f32 v[56:57], s[4:5], v[174:175], v[56:57] op_sel_hi:[0,1,1]
	global_load_dwordx2 v[40:41], v144, s[52:53]
	s_waitcnt vmcnt(15)
	v_readlane_b32 s4, v12, 18
	v_cvt_scalef32_pk_f32_fp4 v[160:161], v38, 1.0
	v_cvt_scalef32_pk_f32_fp4 v[162:163], v38, 1.0 op_sel:[1,0,0]
	v_pk_fma_f32 v[52:53], s[4:5], v[160:161], v[52:53] op_sel_hi:[0,1,1]
	v_cvt_scalef32_pk_f32_fp4 v[164:165], v38, 1.0 op_sel:[0,1,0]
	v_pk_fma_f32 v[50:51], s[4:5], v[162:163], v[50:51] op_sel_hi:[0,1,1]
	v_cvt_scalef32_pk_f32_fp4 v[166:167], v38, 1.0 op_sel:[1,1,0]
	v_pk_fma_f32 v[48:49], s[4:5], v[164:165], v[48:49] op_sel_hi:[0,1,1]
	v_cvt_scalef32_pk_f32_fp4 v[168:169], v39, 1.0
	v_pk_fma_f32 v[46:47], s[4:5], v[166:167], v[46:47] op_sel_hi:[0,1,1]
	v_cvt_scalef32_pk_f32_fp4 v[170:171], v39, 1.0 op_sel:[1,0,0]
	v_pk_fma_f32 v[44:45], s[4:5], v[168:169], v[44:45] op_sel_hi:[0,1,1]
	v_cvt_scalef32_pk_f32_fp4 v[172:173], v39, 1.0 op_sel:[0,1,0]
	v_pk_fma_f32 v[42:43], s[4:5], v[170:171], v[42:43] op_sel_hi:[0,1,1]
	v_cvt_scalef32_pk_f32_fp4 v[174:175], v39, 1.0 op_sel:[1,1,0]
	v_pk_fma_f32 v[54:55], s[4:5], v[172:173], v[54:55] op_sel_hi:[0,1,1]
	v_pk_fma_f32 v[56:57], s[4:5], v[174:175], v[56:57] op_sel_hi:[0,1,1]
	global_load_dwordx2 v[38:39], v145, s[52:53]
	s_waitcnt vmcnt(15)
	v_readlane_b32 s4, v12, 17
	v_cvt_scalef32_pk_f32_fp4 v[160:161], v36, 1.0
	v_cvt_scalef32_pk_f32_fp4 v[162:163], v36, 1.0 op_sel:[1,0,0]
	v_pk_fma_f32 v[52:53], s[4:5], v[160:161], v[52:53] op_sel_hi:[0,1,1]
	v_cvt_scalef32_pk_f32_fp4 v[164:165], v36, 1.0 op_sel:[0,1,0]
	v_pk_fma_f32 v[50:51], s[4:5], v[162:163], v[50:51] op_sel_hi:[0,1,1]
	v_cvt_scalef32_pk_f32_fp4 v[166:167], v36, 1.0 op_sel:[1,1,0]
	v_pk_fma_f32 v[48:49], s[4:5], v[164:165], v[48:49] op_sel_hi:[0,1,1]
	v_cvt_scalef32_pk_f32_fp4 v[168:169], v37, 1.0
	v_pk_fma_f32 v[46:47], s[4:5], v[166:167], v[46:47] op_sel_hi:[0,1,1]
	v_cvt_scalef32_pk_f32_fp4 v[170:171], v37, 1.0 op_sel:[1,0,0]
	v_pk_fma_f32 v[44:45], s[4:5], v[168:169], v[44:45] op_sel_hi:[0,1,1]
	v_cvt_scalef32_pk_f32_fp4 v[172:173], v37, 1.0 op_sel:[0,1,0]
	v_pk_fma_f32 v[42:43], s[4:5], v[170:171], v[42:43] op_sel_hi:[0,1,1]
	v_cvt_scalef32_pk_f32_fp4 v[174:175], v37, 1.0 op_sel:[1,1,0]
	v_pk_fma_f32 v[54:55], s[4:5], v[172:173], v[54:55] op_sel_hi:[0,1,1]
	v_pk_fma_f32 v[56:57], s[4:5], v[174:175], v[56:57] op_sel_hi:[0,1,1]
	global_load_dwordx2 v[36:37], v146, s[52:53]
	s_waitcnt vmcnt(15)
; __device__ __forceinline__ void p3_dots(const u32x2 (&ur)[4], const unsigned* rec, int lane, int (&pt)[4]) {
;     const u32x4 qh = *(const u32x4*)(rec + 256 + lane * 4);
; #pragma unroll
;     for (int u = 0; u < 4; u++) {
;         const int w0 = (int)ur[u].x, w1 = (int)ur[u].y;
;         int dh = __builtin_amdgcn_sdot8(w0, (int)qh.x, 0, false);
;         dh = __builtin_amdgcn_sdot8(w1, (int)qh.z, dh, false);
;         int dl = __builtin_amdgcn_sdot8(w0, (int)qh.y, 0, false);
;         dl = __builtin_amdgcn_sdot8(w1, (int)qh.w, dl, false);
;         pt[u] = (dh << 4) + dl;
;     }
; }
; template <int CTRL> __device__ __forceinline__ int dpp_i(int v) { return __builtin_amdgcn_mov_dpp(v, CTRL, 0xF, 0xF, true); }
; __device__ __forceinline__ int xrow_sum_i(int v) {
;     const auto a = __builtin_amdgcn_permlane16_swap((unsigned)v, (unsigned)v, false, false);
;     v = (int)a[0] + (int)a[1];
;     const auto b = __builtin_amdgcn_permlane32_swap((unsigned)v, (unsigned)v, false, false);
;     return (int)b[0] + (int)b[1];
; }
; __device__ __forceinline__ float p3_weight(const int (&pt)[4], int lane, float sh, int hs8, const P3Sc& sc) {
;     int m2[2], m1;
;     const bool c0 = lane & 1;
; #pragma unroll
;     for (int j = 0; j < 2; j++) { const int keep = c0 ? pt[j + 2] : pt[j], send = c0 ? pt[j] : pt[j + 2]; m2[j] = keep + dpp_i<0xB1>(send); }
;     const bool c1 = lane & 2;
;     { const int keep = c1 ? m2[1] : m2[0], send = c1 ? m2[0] : m2[1]; m1 = keep + dpp_i<0x4E>(send); }
;     m1 += dpp_i<0x124>(m1);
;     m1 += dpp_i<0x128>(m1);
;     m1 = xrow_sum_i(m1);
;     const float aval = (float)(m1 - hs8) * sc.su;
;     return sc.gm * gelu_erf(aval);
; }
; __device__ __forceinline__ void p3_axpy(const u32x2 (&vr)[4], float ws, f32x2 (&acc)[8]) {
; #pragma unroll
;     for (int u = 0; u < 4; u++) {
;         const int la = ((u >> 1) & 1) | ((u & 1) << 1);
;         const float wu = __builtin_bit_cast(float, __builtin_amdgcn_readlane(__builtin_bit_cast(int, ws), la));
;         const f32x2 w2 = {wu, wu};
;         const unsigned vw[2] = {vr[u].x, vr[u].y};
; #pragma unroll
;         for (int i = 0; i < 2; i++) {
;             acc[i * 4 + 0] = __builtin_elementwise_fma(w2, __builtin_amdgcn_cvt_scalef32_pk_f32_fp4(vw[i], 1.0f, 0), acc[i * 4 + 0]);
	v_readlane_b32 s4, v12, 19
	v_cvt_scalef32_pk_f32_fp4 v[160:161], v34, 1.0
	v_cvt_scalef32_pk_f32_fp4 v[162:163], v34, 1.0 op_sel:[1,0,0]
	v_pk_fma_f32 v[52:53], s[4:5], v[160:161], v[52:53] op_sel_hi:[0,1,1]
	v_cvt_scalef32_pk_f32_fp4 v[164:165], v34, 1.0 op_sel:[0,1,0]
	v_pk_fma_f32 v[50:51], s[4:5], v[162:163], v[50:51] op_sel_hi:[0,1,1]
	v_cvt_scalef32_pk_f32_fp4 v[166:167], v34, 1.0 op_sel:[1,1,0]
	v_pk_fma_f32 v[48:49], s[4:5], v[164:165], v[48:49] op_sel_hi:[0,1,1]
	v_cvt_scalef32_pk_f32_fp4 v[168:169], v35, 1.0
	v_pk_fma_f32 v[46:47], s[4:5], v[166:167], v[46:47] op_sel_hi:[0,1,1]
	v_cvt_scalef32_pk_f32_fp4 v[170:171], v35, 1.0 op_sel:[1,0,0]
	v_pk_fma_f32 v[44:45], s[4:5], v[168:169], v[44:45] op_sel_hi:[0,1,1]
	v_cvt_scalef32_pk_f32_fp4 v[172:173], v35, 1.0 op_sel:[0,1,0]
	v_pk_fma_f32 v[42:43], s[4:5], v[170:171], v[42:43] op_sel_hi:[0,1,1]
	v_cvt_scalef32_pk_f32_fp4 v[174:175], v35, 1.0 op_sel:[1,1,0]
	v_pk_fma_f32 v[54:55], s[4:5], v[172:173], v[54:55] op_sel_hi:[0,1,1]
	v_pk_fma_f32 v[56:57], s[4:5], v[174:175], v[56:57] op_sel_hi:[0,1,1]
	global_load_dwordx2 v[34:35], v147, s[52:53]
	s_add_i32 s5, s5, 16
	v_add_u32_e32 v134, s5, v121
	v_add_u32_e32 v135, s5, v137
	ds_read_b128 v[140:143], v134
	ds_read_b128 v[144:147], v134 offset:2560
	ds_read_b128 v[200:203], v134 offset:16
	ds_read_b128 v[204:207], v134 offset:2576
	s_waitcnt vmcnt(16) lgkmcnt(4)
	v_dot8_i32_i4 v12, v184, v4, 0
	v_dot8_i32_i4 v27, v184, v5, 0
	v_dot8_i32_i4 v131, v186, v4, 0
	v_dot8_i32_i4 v132, v186, v5, 0
	v_dot8c_i32_i4_e32 v12, v185, v6
	v_dot8c_i32_i4_e32 v27, v185, v7
	v_dot8c_i32_i4_e32 v131, v187, v6
	v_dot8c_i32_i4_e32 v132, v187, v7
	v_dot8_i32_i4 v133, v188, v4, 0
	v_dot8_i32_i4 v176, v188, v5, 0
	v_dot8_i32_i4 v177, v190, v4, 0
	v_dot8_i32_i4 v178, v190, v5, 0
	v_dot8c_i32_i4_e32 v133, v189, v6
	v_dot8c_i32_i4_e32 v176, v189, v7
	v_dot8c_i32_i4_e32 v177, v191, v6
	v_dot8c_i32_i4_e32 v178, v191, v7
	v_lshl_add_u32 v27, v12, 4, v27
	v_lshl_add_u32 v131, v131, 4, v132
	v_lshl_add_u32 v132, v133, 4, v176
	v_lshl_add_u32 v133, v177, 4, v178
	v_cndmask_b32_e64 v12, v132, v27, s[0:1]
	v_cndmask_b32_e64 v27, v27, v132, s[0:1]
	s_waitcnt lgkmcnt(0)
	v_lshl_add_u32 v200, v200, 9, v136
	v_add_u32_dpp v12, v27, v12 quad_perm:[1,0,3,2] row_mask:0xf bank_mask:0xf bound_ctrl:1
	v_cndmask_b32_e64 v27, v133, v131, s[0:1]
	v_cndmask_b32_e64 v131, v131, v133, s[0:1]
	v_lshl_add_u32 v201, v201, 9, v136
	v_lshl_add_u32 v202, v202, 9, v136
	v_add_u32_dpp v27, v131, v27 quad_perm:[1,0,3,2] row_mask:0xf bank_mask:0xf bound_ctrl:1
	v_cndmask_b32_e64 v131, v27, v12, s[2:3]
	v_cndmask_b32_e64 v12, v12, v27, s[2:3]
	v_lshl_add_u32 v203, v203, 9, v136
	global_load_dwordx2 v[184:185], v200, s[50:51]
	v_add_u32_dpp v12, v12, v131 quad_perm:[2,3,0,1] row_mask:0xf bank_mask:0xf bound_ctrl:1
	global_load_dwordx2 v[186:187], v201, s[50:51]
	global_load_dwordx2 v[188:189], v202, s[50:51]
	v_add_u32_dpp v12, v12, v12 row_ror:4 row_mask:0xf bank_mask:0xf bound_ctrl:1
	global_load_dwordx2 v[190:191], v203, s[50:51]
	s_waitcnt vmcnt(8)
	v_add_u32_dpp v181, v12, v12 row_ror:8 row_mask:0xf bank_mask:0xf bound_ctrl:1
	v_lshl_add_u32 v140, v140, 9, v136
	v_lshl_add_u32 v141, v141, 9, v136
	v_lshl_add_u32 v142, v142, 9, v136
	v_lshl_add_u32 v143, v143, 9, v136
	v_dot8_i32_i4 v12, v192, v0, 0
	v_dot8_i32_i4 v27, v192, v1, 0
	v_dot8_i32_i4 v131, v194, v0, 0
	v_dot8_i32_i4 v132, v194, v1, 0
	v_dot8c_i32_i4_e32 v12, v193, v2
	v_dot8c_i32_i4_e32 v27, v193, v3
	v_dot8c_i32_i4_e32 v131, v195, v2
	v_dot8c_i32_i4_e32 v132, v195, v3
	v_dot8_i32_i4 v133, v196, v0, 0
	v_dot8_i32_i4 v176, v196, v1, 0
	v_dot8_i32_i4 v177, v198, v0, 0
	v_dot8_i32_i4 v178, v198, v1, 0
	v_dot8c_i32_i4_e32 v133, v197, v2
	v_dot8c_i32_i4_e32 v176, v197, v3
	v_dot8c_i32_i4_e32 v177, v199, v2
	v_dot8c_i32_i4_e32 v178, v199, v3
	v_lshl_add_u32 v27, v12, 4, v27
	v_lshl_add_u32 v131, v131, 4, v132
	v_lshl_add_u32 v132, v133, 4, v176
	v_lshl_add_u32 v133, v177, 4, v178
	v_cndmask_b32_e64 v12, v132, v27, s[0:1]
	v_cndmask_b32_e64 v27, v27, v132, s[0:1]
	v_lshl_add_u32 v204, v204, 9, v136
	v_lshl_add_u32 v205, v205, 9, v136
	v_add_u32_dpp v12, v27, v12 quad_perm:[1,0,3,2] row_mask:0xf bank_mask:0xf bound_ctrl:1
	v_cndmask_b32_e64 v27, v133, v131, s[0:1]
	v_cndmask_b32_e64 v131, v131, v133, s[0:1]
	v_lshl_add_u32 v206, v206, 9, v136
	v_lshl_add_u32 v207, v207, 9, v136
	v_add_u32_dpp v27, v131, v27 quad_perm:[1,0,3,2] row_mask:0xf bank_mask:0xf bound_ctrl:1
	v_cndmask_b32_e64 v131, v27, v12, s[2:3]
	v_cndmask_b32_e64 v12, v12, v27, s[2:3]
	global_load_dwordx2 v[192:193], v204, s[50:51]
	global_load_dwordx2 v[194:195], v205, s[50:51]
	v_add_u32_dpp v12, v12, v131 quad_perm:[2,3,0,1] row_mask:0xf bank_mask:0xf bound_ctrl:1
	global_load_dwordx2 v[196:197], v206, s[50:51]
	global_load_dwordx2 v[198:199], v207, s[50:51]
	v_add_u32_dpp v12, v12, v12 row_ror:4 row_mask:0xf bank_mask:0xf bound_ctrl:1
	v_cvt_scalef32_pk_f32_fp4 v[160:161], v72, 1.0
	v_cvt_scalef32_pk_f32_fp4 v[162:163], v72, 1.0 op_sel:[1,0,0]
	v_add_u32_dpp v12, v12, v12 row_ror:8 row_mask:0xf bank_mask:0xf bound_ctrl:1
	v_lshl_add_u32 v144, v144, 9, v136
	v_lshl_add_u32 v145, v145, 9, v136
	v_lshl_add_u32 v146, v146, 9, v136
	v_lshl_add_u32 v147, v147, 9, v136
	v_cvt_scalef32_pk_f32_fp4 v[164:165], v72, 1.0 op_sel:[0,1,0]
	v_cvt_scalef32_pk_f32_fp4 v[166:167], v72, 1.0 op_sel:[1,1,0]
	v_permlane16_swap_b32_e32 v181, v12
	v_add_u32_e32 v12, v181, v12
	v_mov_b32_e32 v27, v12
	v_cvt_scalef32_pk_f32_fp4 v[168:169], v73, 1.0
	v_cvt_scalef32_pk_f32_fp4 v[170:171], v73, 1.0 op_sel:[1,0,0]
	v_permlane32_swap_b32_e32 v12, v27
	v_add_u32_e32 v12, v27, v12
	v_cvt_f32_i32_e32 v12, v12
; template <int CTRL> __device__ __forceinline__ int dpp_i(int v) { return __builtin_amdgcn_mov_dpp(v, CTRL, 0xF, 0xF, true); }
; __device__ __forceinline__ float p3_weight(const int (&pt)[4], int lane, float sh, int hs8, const P3Sc& sc) {
;     int m2[2], m1;
;     const bool c0 = lane & 1;
; #pragma unroll
;     for (int j = 0; j < 2; j++) { const int keep = c0 ? pt[j + 2] : pt[j], send = c0 ? pt[j] : pt[j + 2]; m2[j] = keep + dpp_i<0xB1>(send); }
;     const bool c1 = lane & 2;
;     { const int keep = c1 ? m2[1] : m2[0], send = c1 ? m2[0] : m2[1]; m1 = keep + dpp_i<0x4E>(send); }
;     m1 += dpp_i<0x124>(m1);
;     m1 += dpp_i<0x128>(m1);
;     m1 = xrow_sum_i(m1);
;     const float aval = (float)(m1 - hs8) * sc.su;
;     return sc.gm * gelu_erf(aval);
; }
; __device__ __forceinline__ void p3_axpy(const u32x2 (&vr)[4], float ws, f32x2 (&acc)[8]) {
; #pragma unroll
;     for (int u = 0; u < 4; u++) {
;         const int la = ((u >> 1) & 1) | ((u & 1) << 1);
;         const float wu = __builtin_bit_cast(float, __builtin_amdgcn_readlane(__builtin_bit_cast(int, ws), la));
;         const f32x2 w2 = {wu, wu};
;         const unsigned vw[2] = {vr[u].x, vr[u].y};
; #pragma unroll
;         for (int i = 0; i < 2; i++) {
;             acc[i * 4 + 0] = __builtin_elementwise_fma(w2, __builtin_amdgcn_cvt_scalef32_pk_f32_fp4(vw[i], 1.0f, 0), acc[i * 4 + 0]);
;             acc[i * 4 + 1] = __builtin_elementwise_fma(w2, __builtin_amdgcn_cvt_scalef32_pk_f32_fp4(vw[i], 1.0f, 1), acc[i * 4 + 1]);
;             acc[i * 4 + 2] = __builtin_elementwise_fma(w2, __builtin_amdgcn_cvt_scalef32_pk_f32_fp4(vw[i], 1.0f, 2), acc[i * 4 + 2]);
;             acc[i * 4 + 3] = __builtin_elementwise_fma(w2, __builtin_amdgcn_cvt_scalef32_pk_f32_fp4(vw[i], 1.0f, 3), acc[i * 4 + 3]);
;         }
;     }
; }
	v_mul_f32_e32 v12, v77, v12
	v_fma_f32 v179, |v12|, s39, 1.0
	v_rcp_f32_e32 v179, v179
	v_cmp_gt_f32_e32 vcc, 0, v12
	v_fmamk_f32 v180, v179, 0x3f07dc22, v129
	v_fmaak_f32 v180, v179, v180, 0x3f35f0e3
	v_fmaak_f32 v180, v179, v180, 0xbe11a98e
	v_fmaak_f32 v180, v179, v180, 0x3e027906
	v_mul_f32_e32 v179, v179, v180
	v_mul_f32_e32 v180, v12, v12
	v_mul_f32_e32 v180, 0xbf38aa3b, v180
	v_exp_f32_e32 v180, v180
	v_cvt_scalef32_pk_f32_fp4 v[172:173], v73, 1.0 op_sel:[0,1,0]
	v_mul_f32_e32 v179, v180, v179
	v_mul_f32_e32 v180, v12, v179
	v_fma_f32 v12, -v12, v179, v12
	v_cndmask_b32_e32 v12, v12, v180, vcc
	v_mul_f32_e32 v12, v76, v12
	ds_read2st64_b32 v[76:77], v135 offset1:6
	v_readlane_b32 s4, v12, 0
	v_cvt_scalef32_pk_f32_fp4 v[174:175], v73, 1.0 op_sel:[1,1,0]
	global_load_dwordx2 v[72:73], v140, s[52:53]
	v_pk_fma_f32 v[100:101], s[4:5], v[160:161], v[100:101] op_sel_hi:[0,1,1]
	v_pk_fma_f32 v[98:99], s[4:5], v[162:163], v[98:99] op_sel_hi:[0,1,1]
	v_pk_fma_f32 v[96:97], s[4:5], v[164:165], v[96:97] op_sel_hi:[0,1,1]
	v_pk_fma_f32 v[94:95], s[4:5], v[166:167], v[94:95] op_sel_hi:[0,1,1]
	v_pk_fma_f32 v[92:93], s[4:5], v[168:169], v[92:93] op_sel_hi:[0,1,1]
	v_pk_fma_f32 v[90:91], s[4:5], v[170:171], v[90:91] op_sel_hi:[0,1,1]
	v_pk_fma_f32 v[88:89], s[4:5], v[172:173], v[88:89] op_sel_hi:[0,1,1]
	v_pk_fma_f32 v[86:87], s[4:5], v[174:175], v[86:87] op_sel_hi:[0,1,1]
	v_readlane_b32 s4, v12, 2
	v_cvt_scalef32_pk_f32_fp4 v[160:161], v70, 1.0
	v_cvt_scalef32_pk_f32_fp4 v[162:163], v70, 1.0 op_sel:[1,0,0]
	v_pk_fma_f32 v[100:101], s[4:5], v[160:161], v[100:101] op_sel_hi:[0,1,1]
	v_cvt_scalef32_pk_f32_fp4 v[164:165], v70, 1.0 op_sel:[0,1,0]
	v_pk_fma_f32 v[98:99], s[4:5], v[162:163], v[98:99] op_sel_hi:[0,1,1]
	v_cvt_scalef32_pk_f32_fp4 v[166:167], v70, 1.0 op_sel:[1,1,0]
	v_pk_fma_f32 v[96:97], s[4:5], v[164:165], v[96:97] op_sel_hi:[0,1,1]
	v_cvt_scalef32_pk_f32_fp4 v[168:169], v71, 1.0
	v_pk_fma_f32 v[94:95], s[4:5], v[166:167], v[94:95] op_sel_hi:[0,1,1]
	v_cvt_scalef32_pk_f32_fp4 v[170:171], v71, 1.0 op_sel:[1,0,0]
	v_pk_fma_f32 v[92:93], s[4:5], v[168:169], v[92:93] op_sel_hi:[0,1,1]
	v_cvt_scalef32_pk_f32_fp4 v[172:173], v71, 1.0 op_sel:[0,1,0]
	v_pk_fma_f32 v[90:91], s[4:5], v[170:171], v[90:91] op_sel_hi:[0,1,1]
	v_cvt_scalef32_pk_f32_fp4 v[174:175], v71, 1.0 op_sel:[1,1,0]
	v_pk_fma_f32 v[88:89], s[4:5], v[172:173], v[88:89] op_sel_hi:[0,1,1]
	v_pk_fma_f32 v[86:87], s[4:5], v[174:175], v[86:87] op_sel_hi:[0,1,1]
	global_load_dwordx2 v[70:71], v141, s[52:53]
	v_readlane_b32 s4, v12, 1
	v_cvt_scalef32_pk_f32_fp4 v[160:161], v62, 1.0
	v_cvt_scalef32_pk_f32_fp4 v[162:163], v62, 1.0 op_sel:[1,0,0]
	v_pk_fma_f32 v[100:101], s[4:5], v[160:161], v[100:101] op_sel_hi:[0,1,1]
	v_cvt_scalef32_pk_f32_fp4 v[164:165], v62, 1.0 op_sel:[0,1,0]
	v_pk_fma_f32 v[98:99], s[4:5], v[162:163], v[98:99] op_sel_hi:[0,1,1]
	v_cvt_scalef32_pk_f32_fp4 v[166:167], v62, 1.0 op_sel:[1,1,0]
	v_pk_fma_f32 v[96:97], s[4:5], v[164:165], v[96:97] op_sel_hi:[0,1,1]
	v_cvt_scalef32_pk_f32_fp4 v[168:169], v63, 1.0
	v_pk_fma_f32 v[94:95], s[4:5], v[166:167], v[94:95] op_sel_hi:[0,1,1]
	v_cvt_scalef32_pk_f32_fp4 v[170:171], v63, 1.0 op_sel:[1,0,0]
	v_pk_fma_f32 v[92:93], s[4:5], v[168:169], v[92:93] op_sel_hi:[0,1,1]
	v_cvt_scalef32_pk_f32_fp4 v[172:173], v63, 1.0 op_sel:[0,1,0]
	v_pk_fma_f32 v[90:91], s[4:5], v[170:171], v[90:91] op_sel_hi:[0,1,1]
	v_cvt_scalef32_pk_f32_fp4 v[174:175], v63, 1.0 op_sel:[1,1,0]
	v_pk_fma_f32 v[88:89], s[4:5], v[172:173], v[88:89] op_sel_hi:[0,1,1]
	v_pk_fma_f32 v[86:87], s[4:5], v[174:175], v[86:87] op_sel_hi:[0,1,1]
	global_load_dwordx2 v[62:63], v142, s[52:53]
	v_readlane_b32 s4, v12, 3
	v_cvt_scalef32_pk_f32_fp4 v[160:161], v58, 1.0
	v_cvt_scalef32_pk_f32_fp4 v[162:163], v58, 1.0 op_sel:[1,0,0]
	v_pk_fma_f32 v[100:101], s[4:5], v[160:161], v[100:101] op_sel_hi:[0,1,1]
	v_cvt_scalef32_pk_f32_fp4 v[164:165], v58, 1.0 op_sel:[0,1,0]
	v_pk_fma_f32 v[98:99], s[4:5], v[162:163], v[98:99] op_sel_hi:[0,1,1]
	v_cvt_scalef32_pk_f32_fp4 v[166:167], v58, 1.0 op_sel:[1,1,0]
	v_pk_fma_f32 v[96:97], s[4:5], v[164:165], v[96:97] op_sel_hi:[0,1,1]
	v_cvt_scalef32_pk_f32_fp4 v[168:169], v59, 1.0
	v_pk_fma_f32 v[94:95], s[4:5], v[166:167], v[94:95] op_sel_hi:[0,1,1]
	v_cvt_scalef32_pk_f32_fp4 v[170:171], v59, 1.0 op_sel:[1,0,0]
	v_pk_fma_f32 v[92:93], s[4:5], v[168:169], v[92:93] op_sel_hi:[0,1,1]
	v_cvt_scalef32_pk_f32_fp4 v[172:173], v59, 1.0 op_sel:[0,1,0]
	v_pk_fma_f32 v[90:91], s[4:5], v[170:171], v[90:91] op_sel_hi:[0,1,1]
	v_cvt_scalef32_pk_f32_fp4 v[174:175], v59, 1.0 op_sel:[1,1,0]
	v_pk_fma_f32 v[88:89], s[4:5], v[172:173], v[88:89] op_sel_hi:[0,1,1]
	v_pk_fma_f32 v[86:87], s[4:5], v[174:175], v[86:87] op_sel_hi:[0,1,1]
	global_load_dwordx2 v[58:59], v143, s[52:53]
	s_waitcnt vmcnt(15)
	v_readlane_b32 s4, v12, 16
	v_cvt_scalef32_pk_f32_fp4 v[160:161], v40, 1.0
	v_cvt_scalef32_pk_f32_fp4 v[162:163], v40, 1.0 op_sel:[1,0,0]
	v_pk_fma_f32 v[52:53], s[4:5], v[160:161], v[52:53] op_sel_hi:[0,1,1]
	v_cvt_scalef32_pk_f32_fp4 v[164:165], v40, 1.0 op_sel:[0,1,0]
	v_pk_fma_f32 v[50:51], s[4:5], v[162:163], v[50:51] op_sel_hi:[0,1,1]
	v_cvt_scalef32_pk_f32_fp4 v[166:167], v40, 1.0 op_sel:[1,1,0]
	v_pk_fma_f32 v[48:49], s[4:5], v[164:165], v[48:49] op_sel_hi:[0,1,1]
	v_cvt_scalef32_pk_f32_fp4 v[168:169], v41, 1.0
	v_pk_fma_f32 v[46:47], s[4:5], v[166:167], v[46:47] op_sel_hi:[0,1,1]
	v_cvt_scalef32_pk_f32_fp4 v[170:171], v41, 1.0 op_sel:[1,0,0]
	v_pk_fma_f32 v[44:45], s[4:5], v[168:169], v[44:45] op_sel_hi:[0,1,1]
	v_cvt_scalef32_pk_f32_fp4 v[172:173], v41, 1.0 op_sel:[0,1,0]
	v_pk_fma_f32 v[42:43], s[4:5], v[170:171], v[42:43] op_sel_hi:[0,1,1]
	v_cvt_scalef32_pk_f32_fp4 v[174:175], v41, 1.0 op_sel:[1,1,0]
	v_pk_fma_f32 v[54:55], s[4:5], v[172:173], v[54:55] op_sel_hi:[0,1,1]
	v_pk_fma_f32 v[56:57], s[4:5], v[174:175], v[56:57] op_sel_hi:[0,1,1]
	global_load_dwordx2 v[40:41], v144, s[52:53]
	s_waitcnt vmcnt(15)
; __device__ __forceinline__ void p3_dots(const u32x2 (&ur)[4], const unsigned* rec, int lane, int (&pt)[4]) {
;     const u32x4 qh = *(const u32x4*)(rec + 256 + lane * 4);
; #pragma unroll
;     for (int u = 0; u < 4; u++) {
;         const int w0 = (int)ur[u].x, w1 = (int)ur[u].y;
;         int dh = __builtin_amdgcn_sdot8(w0, (int)qh.x, 0, false);
;         dh = __builtin_amdgcn_sdot8(w1, (int)qh.z, dh, false);
;         int dl = __builtin_amdgcn_sdot8(w0, (int)qh.y, 0, false);
;         dl = __builtin_amdgcn_sdot8(w1, (int)qh.w, dl, false);
;         pt[u] = (dh << 4) + dl;
;     }
; }
; template <int CTRL> __device__ __forceinline__ int dpp_i(int v) { return __builtin_amdgcn_mov_dpp(v, CTRL, 0xF, 0xF, true); }
; __device__ __forceinline__ int xrow_sum_i(int v) {
;     const auto a = __builtin_amdgcn_permlane16_swap((unsigned)v, (unsigned)v, false, false);
;     v = (int)a[0] + (int)a[1];
;     const auto b = __builtin_amdgcn_permlane32_swap((unsigned)v, (unsigned)v, false, false);
;     return (int)b[0] + (int)b[1];
; }
; __device__ __forceinline__ float p3_weight(const int (&pt)[4], int lane, float sh, int hs8, const P3Sc& sc) {
;     int m2[2], m1;
;     const bool c0 = lane & 1;
; #pragma unroll
;     for (int j = 0; j < 2; j++) { const int keep = c0 ? pt[j + 2] : pt[j], send = c0 ? pt[j] : pt[j + 2]; m2[j] = keep + dpp_i<0xB1>(send); }
;     const bool c1 = lane & 2;
;     { const int keep = c1 ? m2[1] : m2[0], send = c1 ? m2[0] : m2[1]; m1 = keep + dpp_i<0x4E>(send); }
;     m1 += dpp_i<0x124>(m1);
;     m1 += dpp_i<0x128>(m1);
;     m1 = xrow_sum_i(m1);
;     const float aval = (float)(m1 - hs8) * sc.su;
;     return sc.gm * gelu_erf(aval);
; }
; __device__ __forceinline__ void p3_axpy(const u32x2 (&vr)[4], float ws, f32x2 (&acc)[8]) {
; #pragma unroll
;     for (int u = 0; u < 4; u++) {
;         const int la = ((u >> 1) & 1) | ((u & 1) << 1);
;         const float wu = __builtin_bit_cast(float, __builtin_amdgcn_readlane(__builtin_bit_cast(int, ws), la));
;         const f32x2 w2 = {wu, wu};
;         const unsigned vw[2] = {vr[u].x, vr[u].y};
; #pragma unroll
;         for (int i = 0; i < 2; i++) {
;             acc[i * 4 + 0] = __builtin_elementwise_fma(w2, __builtin_amdgcn_cvt_scalef32_pk_f32_fp4(vw[i], 1.0f, 0), acc[i * 4 + 0]);
	v_readlane_b32 s4, v12, 18
	v_cvt_scalef32_pk_f32_fp4 v[160:161], v38, 1.0
	v_cvt_scalef32_pk_f32_fp4 v[162:163], v38, 1.0 op_sel:[1,0,0]
	v_pk_fma_f32 v[52:53], s[4:5], v[160:161], v[52:53] op_sel_hi:[0,1,1]
	v_cvt_scalef32_pk_f32_fp4 v[164:165], v38, 1.0 op_sel:[0,1,0]
	v_pk_fma_f32 v[50:51], s[4:5], v[162:163], v[50:51] op_sel_hi:[0,1,1]
	v_cvt_scalef32_pk_f32_fp4 v[166:167], v38, 1.0 op_sel:[1,1,0]
	v_pk_fma_f32 v[48:49], s[4:5], v[164:165], v[48:49] op_sel_hi:[0,1,1]
	v_cvt_scalef32_pk_f32_fp4 v[168:169], v39, 1.0
	v_pk_fma_f32 v[46:47], s[4:5], v[166:167], v[46:47] op_sel_hi:[0,1,1]
	v_cvt_scalef32_pk_f32_fp4 v[170:171], v39, 1.0 op_sel:[1,0,0]
	v_pk_fma_f32 v[44:45], s[4:5], v[168:169], v[44:45] op_sel_hi:[0,1,1]
	v_cvt_scalef32_pk_f32_fp4 v[172:173], v39, 1.0 op_sel:[0,1,0]
	v_pk_fma_f32 v[42:43], s[4:5], v[170:171], v[42:43] op_sel_hi:[0,1,1]
	v_cvt_scalef32_pk_f32_fp4 v[174:175], v39, 1.0 op_sel:[1,1,0]
	v_pk_fma_f32 v[54:55], s[4:5], v[172:173], v[54:55] op_sel_hi:[0,1,1]
	v_pk_fma_f32 v[56:57], s[4:5], v[174:175], v[56:57] op_sel_hi:[0,1,1]
	global_load_dwordx2 v[38:39], v145, s[52:53]
	s_waitcnt vmcnt(15)
	v_readlane_b32 s4, v12, 17
	v_cvt_scalef32_pk_f32_fp4 v[160:161], v36, 1.0
	v_cvt_scalef32_pk_f32_fp4 v[162:163], v36, 1.0 op_sel:[1,0,0]
	v_pk_fma_f32 v[52:53], s[4:5], v[160:161], v[52:53] op_sel_hi:[0,1,1]
	v_cvt_scalef32_pk_f32_fp4 v[164:165], v36, 1.0 op_sel:[0,1,0]
	v_pk_fma_f32 v[50:51], s[4:5], v[162:163], v[50:51] op_sel_hi:[0,1,1]
	v_cvt_scalef32_pk_f32_fp4 v[166:167], v36, 1.0 op_sel:[1,1,0]
	v_pk_fma_f32 v[48:49], s[4:5], v[164:165], v[48:49] op_sel_hi:[0,1,1]
	v_cvt_scalef32_pk_f32_fp4 v[168:169], v37, 1.0
	v_pk_fma_f32 v[46:47], s[4:5], v[166:167], v[46:47] op_sel_hi:[0,1,1]
	v_cvt_scalef32_pk_f32_fp4 v[170:171], v37, 1.0 op_sel:[1,0,0]
	v_pk_fma_f32 v[44:45], s[4:5], v[168:169], v[44:45] op_sel_hi:[0,1,1]
	v_cvt_scalef32_pk_f32_fp4 v[172:173], v37, 1.0 op_sel:[0,1,0]
	v_pk_fma_f32 v[42:43], s[4:5], v[170:171], v[42:43] op_sel_hi:[0,1,1]
	v_cvt_scalef32_pk_f32_fp4 v[174:175], v37, 1.0 op_sel:[1,1,0]
	v_pk_fma_f32 v[54:55], s[4:5], v[172:173], v[54:55] op_sel_hi:[0,1,1]
	v_pk_fma_f32 v[56:57], s[4:5], v[174:175], v[56:57] op_sel_hi:[0,1,1]
	global_load_dwordx2 v[36:37], v146, s[52:53]
	s_waitcnt vmcnt(15)
	v_readlane_b32 s4, v12, 19
	v_cvt_scalef32_pk_f32_fp4 v[160:161], v34, 1.0
	v_cvt_scalef32_pk_f32_fp4 v[162:163], v34, 1.0 op_sel:[1,0,0]
	v_pk_fma_f32 v[52:53], s[4:5], v[160:161], v[52:53] op_sel_hi:[0,1,1]
	v_cvt_scalef32_pk_f32_fp4 v[164:165], v34, 1.0 op_sel:[0,1,0]
	v_pk_fma_f32 v[50:51], s[4:5], v[162:163], v[50:51] op_sel_hi:[0,1,1]
	v_cvt_scalef32_pk_f32_fp4 v[166:167], v34, 1.0 op_sel:[1,1,0]
	v_pk_fma_f32 v[48:49], s[4:5], v[164:165], v[48:49] op_sel_hi:[0,1,1]
	v_cvt_scalef32_pk_f32_fp4 v[168:169], v35, 1.0
	v_pk_fma_f32 v[46:47], s[4:5], v[166:167], v[46:47] op_sel_hi:[0,1,1]
	v_cvt_scalef32_pk_f32_fp4 v[170:171], v35, 1.0 op_sel:[1,0,0]
	v_pk_fma_f32 v[44:45], s[4:5], v[168:169], v[44:45] op_sel_hi:[0,1,1]
	v_cvt_scalef32_pk_f32_fp4 v[172:173], v35, 1.0 op_sel:[0,1,0]
	v_pk_fma_f32 v[42:43], s[4:5], v[170:171], v[42:43] op_sel_hi:[0,1,1]
	v_cvt_scalef32_pk_f32_fp4 v[174:175], v35, 1.0 op_sel:[1,1,0]
	v_pk_fma_f32 v[54:55], s[4:5], v[172:173], v[54:55] op_sel_hi:[0,1,1]
	v_pk_fma_f32 v[56:57], s[4:5], v[174:175], v[56:57] op_sel_hi:[0,1,1]
	global_load_dwordx2 v[34:35], v147, s[52:53]
	s_add_i32 s5, s5, 16
	s_cmpk_eq_i32 s5, 0x1e0
	s_cbranch_scc0 .LBB0_1075
	v_add_u32_e32 v134, s5, v121
	v_add_u32_e32 v135, s5, v137
	ds_read_b128 v[140:143], v134
	ds_read_b128 v[144:147], v134 offset:2560
	s_waitcnt vmcnt(16) lgkmcnt(2)
	v_dot8_i32_i4 v12, v80, v4, 0
	v_dot8_i32_i4 v27, v80, v5, 0
	v_dot8_i32_i4 v131, v74, v4, 0
	v_dot8_i32_i4 v132, v74, v5, 0
	v_dot8c_i32_i4_e32 v12, v81, v6
	v_dot8c_i32_i4_e32 v27, v81, v7
	v_dot8c_i32_i4_e32 v131, v75, v6
	v_dot8c_i32_i4_e32 v132, v75, v7
	v_dot8_i32_i4 v133, v84, v4, 0
	v_dot8_i32_i4 v176, v84, v5, 0
	v_dot8_i32_i4 v177, v82, v4, 0
	v_dot8_i32_i4 v178, v82, v5, 0
	v_dot8c_i32_i4_e32 v133, v85, v6
	v_dot8c_i32_i4_e32 v176, v85, v7
	v_dot8c_i32_i4_e32 v177, v83, v6
	v_dot8c_i32_i4_e32 v178, v83, v7
	v_lshl_add_u32 v27, v12, 4, v27
	v_lshl_add_u32 v131, v131, 4, v132
	v_lshl_add_u32 v132, v133, 4, v176
	v_lshl_add_u32 v133, v177, 4, v178
	v_cndmask_b32_e64 v12, v132, v27, s[0:1]
	v_cndmask_b32_e64 v27, v27, v132, s[0:1]
	s_waitcnt lgkmcnt(0)
	v_lshl_add_u32 v140, v140, 9, v136
	v_add_u32_dpp v12, v27, v12 quad_perm:[1,0,3,2] row_mask:0xf bank_mask:0xf bound_ctrl:1
	v_cndmask_b32_e64 v27, v133, v131, s[0:1]
	v_cndmask_b32_e64 v131, v131, v133, s[0:1]
	v_lshl_add_u32 v141, v141, 9, v136
	v_lshl_add_u32 v142, v142, 9, v136
	v_add_u32_dpp v27, v131, v27 quad_perm:[1,0,3,2] row_mask:0xf bank_mask:0xf bound_ctrl:1
	v_cndmask_b32_e64 v131, v27, v12, s[2:3]
	v_cndmask_b32_e64 v12, v12, v27, s[2:3]
	v_lshl_add_u32 v143, v143, 9, v136
	s_nop 0
	v_add_u32_dpp v12, v12, v131 quad_perm:[2,3,0,1] row_mask:0xf bank_mask:0xf bound_ctrl:1
	s_nop 0
	s_nop 0
	v_add_u32_dpp v12, v12, v12 row_ror:4 row_mask:0xf bank_mask:0xf bound_ctrl:1
	s_nop 0
	s_waitcnt vmcnt(4)
; __device__ __forceinline__ void p3_dots(const u32x2 (&ur)[4], const unsigned* rec, int lane, int (&pt)[4]) {
;     const u32x4 qh = *(const u32x4*)(rec + 256 + lane * 4);
; #pragma unroll
;     for (int u = 0; u < 4; u++) {
;         const int w0 = (int)ur[u].x, w1 = (int)ur[u].y;
;         int dh = __builtin_amdgcn_sdot8(w0, (int)qh.x, 0, false);
;         dh = __builtin_amdgcn_sdot8(w1, (int)qh.z, dh, false);
;         int dl = __builtin_amdgcn_sdot8(w0, (int)qh.y, 0, false);
;         dl = __builtin_amdgcn_sdot8(w1, (int)qh.w, dl, false);
;         pt[u] = (dh << 4) + dl;
;     }
; }
; template <int CTRL> __device__ __forceinline__ int dpp_i(int v) { return __builtin_amdgcn_mov_dpp(v, CTRL, 0xF, 0xF, true); }
; __device__ __forceinline__ int xrow_sum_i(int v) {
;     const auto a = __builtin_amdgcn_permlane16_swap((unsigned)v, (unsigned)v, false, false);
;     v = (int)a[0] + (int)a[1];
;     const auto b = __builtin_amdgcn_permlane32_swap((unsigned)v, (unsigned)v, false, false);
;     return (int)b[0] + (int)b[1];
; }
; __device__ __forceinline__ float p3_weight(const int (&pt)[4], int lane, float sh, int hs8, const P3Sc& sc) {
;     int m2[2], m1;
;     const bool c0 = lane & 1;
; #pragma unroll
;     for (int j = 0; j < 2; j++) { const int keep = c0 ? pt[j + 2] : pt[j], send = c0 ? pt[j] : pt[j + 2]; m2[j] = keep + dpp_i<0xB1>(send); }
;     const bool c1 = lane & 2;
;     { const int keep = c1 ? m2[1] : m2[0], send = c1 ? m2[0] : m2[1]; m1 = keep + dpp_i<0x4E>(send); }
;     m1 += dpp_i<0x124>(m1);
;     m1 += dpp_i<0x128>(m1);
;     m1 = xrow_sum_i(m1);
;     const float aval = (float)(m1 - hs8) * sc.su;
;     return sc.gm * gelu_erf(aval);
; }
; __device__ __forceinline__ void p3_axpy(const u32x2 (&vr)[4], float ws, f32x2 (&acc)[8]) {
; #pragma unroll
;     for (int u = 0; u < 4; u++) {
;         const int la = ((u >> 1) & 1) | ((u & 1) << 1);
;         const float wu = __builtin_bit_cast(float, __builtin_amdgcn_readlane(__builtin_bit_cast(int, ws), la));
;         const f32x2 w2 = {wu, wu};
;         const unsigned vw[2] = {vr[u].x, vr[u].y};
; #pragma unroll
;         for (int i = 0; i < 2; i++) {
;             acc[i * 4 + 0] = __builtin_elementwise_fma(w2, __builtin_amdgcn_cvt_scalef32_pk_f32_fp4(vw[i], 1.0f, 0), acc[i * 4 + 0]);
	v_add_u32_dpp v181, v12, v12 row_ror:8 row_mask:0xf bank_mask:0xf bound_ctrl:1
	v_dot8_i32_i4 v12, v66, v0, 0
	v_dot8_i32_i4 v27, v66, v1, 0
	v_dot8_i32_i4 v131, v60, v0, 0
	v_dot8_i32_i4 v132, v60, v1, 0
	v_dot8c_i32_i4_e32 v12, v67, v2
	v_dot8c_i32_i4_e32 v27, v67, v3
	v_dot8c_i32_i4_e32 v131, v61, v2
	v_dot8c_i32_i4_e32 v132, v61, v3
	v_dot8_i32_i4 v133, v68, v0, 0
	v_dot8_i32_i4 v176, v68, v1, 0
	v_dot8_i32_i4 v177, v64, v0, 0
	v_dot8_i32_i4 v178, v64, v1, 0
	v_dot8c_i32_i4_e32 v133, v69, v2
	v_dot8c_i32_i4_e32 v176, v69, v3
	v_dot8c_i32_i4_e32 v177, v65, v2
	v_dot8c_i32_i4_e32 v178, v65, v3
	v_lshl_add_u32 v27, v12, 4, v27
	v_lshl_add_u32 v131, v131, 4, v132
	v_lshl_add_u32 v132, v133, 4, v176
	v_lshl_add_u32 v133, v177, 4, v178
	v_cndmask_b32_e64 v12, v132, v27, s[0:1]
	v_cndmask_b32_e64 v27, v27, v132, s[0:1]
	v_lshl_add_u32 v144, v144, 9, v136
	v_lshl_add_u32 v145, v145, 9, v136
	v_add_u32_dpp v12, v27, v12 quad_perm:[1,0,3,2] row_mask:0xf bank_mask:0xf bound_ctrl:1
	v_cndmask_b32_e64 v27, v133, v131, s[0:1]
	v_cndmask_b32_e64 v131, v131, v133, s[0:1]
	v_lshl_add_u32 v146, v146, 9, v136
	v_lshl_add_u32 v147, v147, 9, v136
	v_add_u32_dpp v27, v131, v27 quad_perm:[1,0,3,2] row_mask:0xf bank_mask:0xf bound_ctrl:1
	v_cndmask_b32_e64 v131, v27, v12, s[2:3]
	v_cndmask_b32_e64 v12, v12, v27, s[2:3]
	s_nop 0
	s_nop 0
	v_add_u32_dpp v12, v12, v131 quad_perm:[2,3,0,1] row_mask:0xf bank_mask:0xf bound_ctrl:1
	s_nop 0
	s_nop 0
	v_add_u32_dpp v12, v12, v12 row_ror:4 row_mask:0xf bank_mask:0xf bound_ctrl:1
	v_cvt_scalef32_pk_f32_fp4 v[160:161], v72, 1.0
	v_cvt_scalef32_pk_f32_fp4 v[162:163], v72, 1.0 op_sel:[1,0,0]
	v_add_u32_dpp v12, v12, v12 row_ror:8 row_mask:0xf bank_mask:0xf bound_ctrl:1
	v_cvt_scalef32_pk_f32_fp4 v[164:165], v72, 1.0 op_sel:[0,1,0]
	v_cvt_scalef32_pk_f32_fp4 v[166:167], v72, 1.0 op_sel:[1,1,0]
	v_permlane16_swap_b32_e32 v181, v12
	v_add_u32_e32 v12, v181, v12
	v_mov_b32_e32 v27, v12
	v_cvt_scalef32_pk_f32_fp4 v[168:169], v73, 1.0
	v_cvt_scalef32_pk_f32_fp4 v[170:171], v73, 1.0 op_sel:[1,0,0]
	v_permlane32_swap_b32_e32 v12, v27
	v_add_u32_e32 v12, v27, v12
	v_cvt_f32_i32_e32 v12, v12
	v_mul_f32_e32 v12, v77, v12
	v_fma_f32 v179, |v12|, s39, 1.0
	v_rcp_f32_e32 v179, v179
	v_cmp_gt_f32_e32 vcc, 0, v12
	v_fmamk_f32 v180, v179, 0x3f07dc22, v129
	v_fmaak_f32 v180, v179, v180, 0x3f35f0e3
	v_fmaak_f32 v180, v179, v180, 0xbe11a98e
	v_fmaak_f32 v180, v179, v180, 0x3e027906
	v_mul_f32_e32 v179, v179, v180
	v_mul_f32_e32 v180, v12, v12
	v_mul_f32_e32 v180, 0xbf38aa3b, v180
	v_exp_f32_e32 v180, v180
	v_cvt_scalef32_pk_f32_fp4 v[172:173], v73, 1.0 op_sel:[0,1,0]
	v_mul_f32_e32 v179, v180, v179
	v_mul_f32_e32 v180, v12, v179
	v_fma_f32 v12, -v12, v179, v12
	v_cndmask_b32_e32 v12, v12, v180, vcc
	v_mul_f32_e32 v12, v76, v12
	ds_read2st64_b32 v[76:77], v135 offset1:6
	v_readlane_b32 s4, v12, 0
	v_cvt_scalef32_pk_f32_fp4 v[174:175], v73, 1.0 op_sel:[1,1,0]
	global_load_dwordx2 v[72:73], v140, s[52:53]
	v_pk_fma_f32 v[100:101], s[4:5], v[160:161], v[100:101] op_sel_hi:[0,1,1]
	v_pk_fma_f32 v[98:99], s[4:5], v[162:163], v[98:99] op_sel_hi:[0,1,1]
	v_pk_fma_f32 v[96:97], s[4:5], v[164:165], v[96:97] op_sel_hi:[0,1,1]
	v_pk_fma_f32 v[94:95], s[4:5], v[166:167], v[94:95] op_sel_hi:[0,1,1]
	v_pk_fma_f32 v[92:93], s[4:5], v[168:169], v[92:93] op_sel_hi:[0,1,1]
	v_pk_fma_f32 v[90:91], s[4:5], v[170:171], v[90:91] op_sel_hi:[0,1,1]
	v_pk_fma_f32 v[88:89], s[4:5], v[172:173], v[88:89] op_sel_hi:[0,1,1]
	v_pk_fma_f32 v[86:87], s[4:5], v[174:175], v[86:87] op_sel_hi:[0,1,1]
	v_readlane_b32 s4, v12, 2
	v_cvt_scalef32_pk_f32_fp4 v[160:161], v70, 1.0
	v_cvt_scalef32_pk_f32_fp4 v[162:163], v70, 1.0 op_sel:[1,0,0]
	v_pk_fma_f32 v[100:101], s[4:5], v[160:161], v[100:101] op_sel_hi:[0,1,1]
	v_cvt_scalef32_pk_f32_fp4 v[164:165], v70, 1.0 op_sel:[0,1,0]
	v_pk_fma_f32 v[98:99], s[4:5], v[162:163], v[98:99] op_sel_hi:[0,1,1]
	v_cvt_scalef32_pk_f32_fp4 v[166:167], v70, 1.0 op_sel:[1,1,0]
	v_pk_fma_f32 v[96:97], s[4:5], v[164:165], v[96:97] op_sel_hi:[0,1,1]
	v_cvt_scalef32_pk_f32_fp4 v[168:169], v71, 1.0
	v_pk_fma_f32 v[94:95], s[4:5], v[166:167], v[94:95] op_sel_hi:[0,1,1]
	v_cvt_scalef32_pk_f32_fp4 v[170:171], v71, 1.0 op_sel:[1,0,0]
	v_pk_fma_f32 v[92:93], s[4:5], v[168:169], v[92:93] op_sel_hi:[0,1,1]
	v_cvt_scalef32_pk_f32_fp4 v[172:173], v71, 1.0 op_sel:[0,1,0]
	v_pk_fma_f32 v[90:91], s[4:5], v[170:171], v[90:91] op_sel_hi:[0,1,1]
	v_cvt_scalef32_pk_f32_fp4 v[174:175], v71, 1.0 op_sel:[1,1,0]
	v_pk_fma_f32 v[88:89], s[4:5], v[172:173], v[88:89] op_sel_hi:[0,1,1]
	v_pk_fma_f32 v[86:87], s[4:5], v[174:175], v[86:87] op_sel_hi:[0,1,1]
	global_load_dwordx2 v[70:71], v141, s[52:53]
	v_readlane_b32 s4, v12, 1
	v_cvt_scalef32_pk_f32_fp4 v[160:161], v62, 1.0
	v_cvt_scalef32_pk_f32_fp4 v[162:163], v62, 1.0 op_sel:[1,0,0]
	v_pk_fma_f32 v[100:101], s[4:5], v[160:161], v[100:101] op_sel_hi:[0,1,1]
	v_cvt_scalef32_pk_f32_fp4 v[164:165], v62, 1.0 op_sel:[0,1,0]
	v_pk_fma_f32 v[98:99], s[4:5], v[162:163], v[98:99] op_sel_hi:[0,1,1]
	v_cvt_scalef32_pk_f32_fp4 v[166:167], v62, 1.0 op_sel:[1,1,0]
	v_pk_fma_f32 v[96:97], s[4:5], v[164:165], v[96:97] op_sel_hi:[0,1,1]
	v_cvt_scalef32_pk_f32_fp4 v[168:169], v63, 1.0
	v_pk_fma_f32 v[94:95], s[4:5], v[166:167], v[94:95] op_sel_hi:[0,1,1]
	v_cvt_scalef32_pk_f32_fp4 v[170:171], v63, 1.0 op_sel:[1,0,0]
	v_pk_fma_f32 v[92:93], s[4:5], v[168:169], v[92:93] op_sel_hi:[0,1,1]
	v_cvt_scalef32_pk_f32_fp4 v[172:173], v63, 1.0 op_sel:[0,1,0]
	v_pk_fma_f32 v[90:91], s[4:5], v[170:171], v[90:91] op_sel_hi:[0,1,1]
	v_cvt_scalef32_pk_f32_fp4 v[174:175], v63, 1.0 op_sel:[1,1,0]
	v_pk_fma_f32 v[88:89], s[4:5], v[172:173], v[88:89] op_sel_hi:[0,1,1]
	v_pk_fma_f32 v[86:87], s[4:5], v[174:175], v[86:87] op_sel_hi:[0,1,1]
	global_load_dwordx2 v[62:63], v142, s[52:53]
	v_readlane_b32 s4, v12, 3
	v_cvt_scalef32_pk_f32_fp4 v[160:161], v58, 1.0
	v_cvt_scalef32_pk_f32_fp4 v[162:163], v58, 1.0 op_sel:[1,0,0]
	v_pk_fma_f32 v[100:101], s[4:5], v[160:161], v[100:101] op_sel_hi:[0,1,1]
	v_cvt_scalef32_pk_f32_fp4 v[164:165], v58, 1.0 op_sel:[0,1,0]
	v_pk_fma_f32 v[98:99], s[4:5], v[162:163], v[98:99] op_sel_hi:[0,1,1]
	v_cvt_scalef32_pk_f32_fp4 v[166:167], v58, 1.0 op_sel:[1,1,0]
	v_pk_fma_f32 v[96:97], s[4:5], v[164:165], v[96:97] op_sel_hi:[0,1,1]
	v_cvt_scalef32_pk_f32_fp4 v[168:169], v59, 1.0
	v_pk_fma_f32 v[94:95], s[4:5], v[166:167], v[94:95] op_sel_hi:[0,1,1]
	v_cvt_scalef32_pk_f32_fp4 v[170:171], v59, 1.0 op_sel:[1,0,0]
	v_pk_fma_f32 v[92:93], s[4:5], v[168:169], v[92:93] op_sel_hi:[0,1,1]
	v_cvt_scalef32_pk_f32_fp4 v[172:173], v59, 1.0 op_sel:[0,1,0]
	v_pk_fma_f32 v[90:91], s[4:5], v[170:171], v[90:91] op_sel_hi:[0,1,1]
	v_cvt_scalef32_pk_f32_fp4 v[174:175], v59, 1.0 op_sel:[1,1,0]
	v_pk_fma_f32 v[88:89], s[4:5], v[172:173], v[88:89] op_sel_hi:[0,1,1]
	v_pk_fma_f32 v[86:87], s[4:5], v[174:175], v[86:87] op_sel_hi:[0,1,1]
	global_load_dwordx2 v[58:59], v143, s[52:53]
	s_waitcnt vmcnt(7)
; __device__ __forceinline__ void p3_load_u(u32x2 (&ur)[4], P3Sc& sc, const unsigned char* __restrict__ UQ, const float* __restrict__ tsc,
;                                           int lane, int ul, int g, const unsigned* rec) {
; #pragma unroll
;     for (int u = 0; u < 4; u++) ur[u] = *(const u32x2*)(UQ + (size_t)rec[4 * g + u] * 512 + lane * 8);
;     sc.gm = __uint_as_float(rec[128 + 4 * g + ul]);
;     sc.su = __uint_as_float(rec[512 + 4 * g + ul]);
;     sc.sv = 1.f;
; }
; __device__ __forceinline__ void p3_axpy(const u32x2 (&vr)[4], float ws, f32x2 (&acc)[8]) {
; #pragma unroll
;     for (int u = 0; u < 4; u++) {
;         const int la = ((u >> 1) & 1) | ((u & 1) << 1);
;         const float wu = __builtin_bit_cast(float, __builtin_amdgcn_readlane(__builtin_bit_cast(int, ws), la));
;         const f32x2 w2 = {wu, wu};
;         const unsigned vw[2] = {vr[u].x, vr[u].y};
; #pragma unroll
;         for (int i = 0; i < 2; i++) {
;             acc[i * 4 + 0] = __builtin_elementwise_fma(w2, __builtin_amdgcn_cvt_scalef32_pk_f32_fp4(vw[i], 1.0f, 0), acc[i * 4 + 0]);
;             acc[i * 4 + 1] = __builtin_elementwise_fma(w2, __builtin_amdgcn_cvt_scalef32_pk_f32_fp4(vw[i], 1.0f, 1), acc[i * 4 + 1]);
;             acc[i * 4 + 2] = __builtin_elementwise_fma(w2, __builtin_amdgcn_cvt_scalef32_pk_f32_fp4(vw[i], 1.0f, 2), acc[i * 4 + 2]);
;             acc[i * 4 + 3] = __builtin_elementwise_fma(w2, __builtin_amdgcn_cvt_scalef32_pk_f32_fp4(vw[i], 1.0f, 3), acc[i * 4 + 3]);
;         }
;     }
; }
	v_readlane_b32 s4, v12, 16
	v_cvt_scalef32_pk_f32_fp4 v[160:161], v40, 1.0
	v_cvt_scalef32_pk_f32_fp4 v[162:163], v40, 1.0 op_sel:[1,0,0]
	v_pk_fma_f32 v[52:53], s[4:5], v[160:161], v[52:53] op_sel_hi:[0,1,1]
	v_cvt_scalef32_pk_f32_fp4 v[164:165], v40, 1.0 op_sel:[0,1,0]
	v_pk_fma_f32 v[50:51], s[4:5], v[162:163], v[50:51] op_sel_hi:[0,1,1]
	v_cvt_scalef32_pk_f32_fp4 v[166:167], v40, 1.0 op_sel:[1,1,0]
	v_pk_fma_f32 v[48:49], s[4:5], v[164:165], v[48:49] op_sel_hi:[0,1,1]
	v_cvt_scalef32_pk_f32_fp4 v[168:169], v41, 1.0
	v_pk_fma_f32 v[46:47], s[4:5], v[166:167], v[46:47] op_sel_hi:[0,1,1]
	v_cvt_scalef32_pk_f32_fp4 v[170:171], v41, 1.0 op_sel:[1,0,0]
	v_pk_fma_f32 v[44:45], s[4:5], v[168:169], v[44:45] op_sel_hi:[0,1,1]
	v_cvt_scalef32_pk_f32_fp4 v[172:173], v41, 1.0 op_sel:[0,1,0]
	v_pk_fma_f32 v[42:43], s[4:5], v[170:171], v[42:43] op_sel_hi:[0,1,1]
	v_cvt_scalef32_pk_f32_fp4 v[174:175], v41, 1.0 op_sel:[1,1,0]
	v_pk_fma_f32 v[54:55], s[4:5], v[172:173], v[54:55] op_sel_hi:[0,1,1]
	v_pk_fma_f32 v[56:57], s[4:5], v[174:175], v[56:57] op_sel_hi:[0,1,1]
	global_load_dwordx2 v[40:41], v144, s[52:53]
	s_waitcnt vmcnt(7)
	v_readlane_b32 s4, v12, 18
	v_cvt_scalef32_pk_f32_fp4 v[160:161], v38, 1.0
	v_cvt_scalef32_pk_f32_fp4 v[162:163], v38, 1.0 op_sel:[1,0,0]
	v_pk_fma_f32 v[52:53], s[4:5], v[160:161], v[52:53] op_sel_hi:[0,1,1]
	v_cvt_scalef32_pk_f32_fp4 v[164:165], v38, 1.0 op_sel:[0,1,0]
	v_pk_fma_f32 v[50:51], s[4:5], v[162:163], v[50:51] op_sel_hi:[0,1,1]
	v_cvt_scalef32_pk_f32_fp4 v[166:167], v38, 1.0 op_sel:[1,1,0]
	v_pk_fma_f32 v[48:49], s[4:5], v[164:165], v[48:49] op_sel_hi:[0,1,1]
	v_cvt_scalef32_pk_f32_fp4 v[168:169], v39, 1.0
	v_pk_fma_f32 v[46:47], s[4:5], v[166:167], v[46:47] op_sel_hi:[0,1,1]
	v_cvt_scalef32_pk_f32_fp4 v[170:171], v39, 1.0 op_sel:[1,0,0]
	v_pk_fma_f32 v[44:45], s[4:5], v[168:169], v[44:45] op_sel_hi:[0,1,1]
	v_cvt_scalef32_pk_f32_fp4 v[172:173], v39, 1.0 op_sel:[0,1,0]
	v_pk_fma_f32 v[42:43], s[4:5], v[170:171], v[42:43] op_sel_hi:[0,1,1]
	v_cvt_scalef32_pk_f32_fp4 v[174:175], v39, 1.0 op_sel:[1,1,0]
	v_pk_fma_f32 v[54:55], s[4:5], v[172:173], v[54:55] op_sel_hi:[0,1,1]
	v_pk_fma_f32 v[56:57], s[4:5], v[174:175], v[56:57] op_sel_hi:[0,1,1]
	global_load_dwordx2 v[38:39], v145, s[52:53]
	s_waitcnt vmcnt(7)
	v_readlane_b32 s4, v12, 17
	v_cvt_scalef32_pk_f32_fp4 v[160:161], v36, 1.0
	v_cvt_scalef32_pk_f32_fp4 v[162:163], v36, 1.0 op_sel:[1,0,0]
	v_pk_fma_f32 v[52:53], s[4:5], v[160:161], v[52:53] op_sel_hi:[0,1,1]
	v_cvt_scalef32_pk_f32_fp4 v[164:165], v36, 1.0 op_sel:[0,1,0]
	v_pk_fma_f32 v[50:51], s[4:5], v[162:163], v[50:51] op_sel_hi:[0,1,1]
	v_cvt_scalef32_pk_f32_fp4 v[166:167], v36, 1.0 op_sel:[1,1,0]
	v_pk_fma_f32 v[48:49], s[4:5], v[164:165], v[48:49] op_sel_hi:[0,1,1]
	v_cvt_scalef32_pk_f32_fp4 v[168:169], v37, 1.0
	v_pk_fma_f32 v[46:47], s[4:5], v[166:167], v[46:47] op_sel_hi:[0,1,1]
	v_cvt_scalef32_pk_f32_fp4 v[170:171], v37, 1.0 op_sel:[1,0,0]
	v_pk_fma_f32 v[44:45], s[4:5], v[168:169], v[44:45] op_sel_hi:[0,1,1]
	v_cvt_scalef32_pk_f32_fp4 v[172:173], v37, 1.0 op_sel:[0,1,0]
	v_pk_fma_f32 v[42:43], s[4:5], v[170:171], v[42:43] op_sel_hi:[0,1,1]
	v_cvt_scalef32_pk_f32_fp4 v[174:175], v37, 1.0 op_sel:[1,1,0]
	v_pk_fma_f32 v[54:55], s[4:5], v[172:173], v[54:55] op_sel_hi:[0,1,1]
	v_pk_fma_f32 v[56:57], s[4:5], v[174:175], v[56:57] op_sel_hi:[0,1,1]
	global_load_dwordx2 v[36:37], v146, s[52:53]
	s_waitcnt vmcnt(7)
	v_readlane_b32 s4, v12, 19
	v_cvt_scalef32_pk_f32_fp4 v[160:161], v34, 1.0
	v_cvt_scalef32_pk_f32_fp4 v[162:163], v34, 1.0 op_sel:[1,0,0]
	v_pk_fma_f32 v[52:53], s[4:5], v[160:161], v[52:53] op_sel_hi:[0,1,1]
	v_cvt_scalef32_pk_f32_fp4 v[164:165], v34, 1.0 op_sel:[0,1,0]
	v_pk_fma_f32 v[50:51], s[4:5], v[162:163], v[50:51] op_sel_hi:[0,1,1]
	v_cvt_scalef32_pk_f32_fp4 v[166:167], v34, 1.0 op_sel:[1,1,0]
	v_pk_fma_f32 v[48:49], s[4:5], v[164:165], v[48:49] op_sel_hi:[0,1,1]
	v_cvt_scalef32_pk_f32_fp4 v[168:169], v35, 1.0
	v_pk_fma_f32 v[46:47], s[4:5], v[166:167], v[46:47] op_sel_hi:[0,1,1]
	v_cvt_scalef32_pk_f32_fp4 v[170:171], v35, 1.0 op_sel:[1,0,0]
	v_pk_fma_f32 v[44:45], s[4:5], v[168:169], v[44:45] op_sel_hi:[0,1,1]
	v_cvt_scalef32_pk_f32_fp4 v[172:173], v35, 1.0 op_sel:[0,1,0]
	v_pk_fma_f32 v[42:43], s[4:5], v[170:171], v[42:43] op_sel_hi:[0,1,1]
	v_cvt_scalef32_pk_f32_fp4 v[174:175], v35, 1.0 op_sel:[1,1,0]
	v_pk_fma_f32 v[54:55], s[4:5], v[172:173], v[54:55] op_sel_hi:[0,1,1]
	v_pk_fma_f32 v[56:57], s[4:5], v[174:175], v[56:57] op_sel_hi:[0,1,1]
	global_load_dwordx2 v[34:35], v147, s[52:53]
	s_add_i32 s5, s5, 16
	v_add_u32_e32 v135, 0x1e0, v120
	ds_read2st64_b32 v[104:105], v135 offset1:6
	ds_read2st64_b32 v[102:103], v135 offset0:10 offset1:16
	s_waitcnt vmcnt(0) lgkmcnt(0)
	v_mov_b32_e32 v80, v184
	v_mov_b32_e32 v81, v185
	v_mov_b32_e32 v74, v186
	v_mov_b32_e32 v75, v187
	v_mov_b32_e32 v84, v188
	v_mov_b32_e32 v85, v189
	v_mov_b32_e32 v82, v190
	v_mov_b32_e32 v83, v191
	v_mov_b32_e32 v66, v192
	v_mov_b32_e32 v67, v193
	v_mov_b32_e32 v60, v194
	v_mov_b32_e32 v61, v195
	v_mov_b32_e32 v68, v196
	v_mov_b32_e32 v69, v197
	v_mov_b32_e32 v64, v198
	v_mov_b32_e32 v65, v199
	v_mov_b32_e32 v12, v13
	v_mov_b32_e32 v27, v13
	s_waitcnt vmcnt(8)
; __device__ __forceinline__ void p3_dots(const u32x2 (&ur)[4], const unsigned* rec, int lane, int (&pt)[4]) {
;     const u32x4 qh = *(const u32x4*)(rec + 256 + lane * 4);
; #pragma unroll
;     for (int u = 0; u < 4; u++) {
;         const int w0 = (int)ur[u].x, w1 = (int)ur[u].y;
;         int dh = __builtin_amdgcn_sdot8(w0, (int)qh.x, 0, false);
;         dh = __builtin_amdgcn_sdot8(w1, (int)qh.z, dh, false);
;         int dl = __builtin_amdgcn_sdot8(w0, (int)qh.y, 0, false);
;         dl = __builtin_amdgcn_sdot8(w1, (int)qh.w, dl, false);
;         pt[u] = (dh << 4) + dl;
;     }
; }
; template <int CTRL> __device__ __forceinline__ int dpp_i(int v) { return __builtin_amdgcn_mov_dpp(v, CTRL, 0xF, 0xF, true); }
; __device__ __forceinline__ int xrow_sum_i(int v) {
;     const auto a = __builtin_amdgcn_permlane16_swap((unsigned)v, (unsigned)v, false, false);
;     v = (int)a[0] + (int)a[1];
;     const auto b = __builtin_amdgcn_permlane32_swap((unsigned)v, (unsigned)v, false, false);
;     return (int)b[0] + (int)b[1];
; }
; __device__ __forceinline__ float p3_weight(const int (&pt)[4], int lane, float sh, int hs8, const P3Sc& sc) {
;     int m2[2], m1;
;     const bool c0 = lane & 1;
; #pragma unroll
;     for (int j = 0; j < 2; j++) { const int keep = c0 ? pt[j + 2] : pt[j], send = c0 ? pt[j] : pt[j + 2]; m2[j] = keep + dpp_i<0xB1>(send); }
;     const bool c1 = lane & 2;
;     { const int keep = c1 ? m2[1] : m2[0], send = c1 ? m2[0] : m2[1]; m1 = keep + dpp_i<0x4E>(send); }
;     m1 += dpp_i<0x124>(m1);
;     m1 += dpp_i<0x128>(m1);
;     m1 = xrow_sum_i(m1);
;     const float aval = (float)(m1 - hs8) * sc.su;
;     return sc.gm * gelu_erf(aval);
; }
; __device__ __forceinline__ void p3_axpy(const u32x2 (&vr)[4], float ws, f32x2 (&acc)[8]) {
; #pragma unroll
;     for (int u = 0; u < 4; u++) {
;         const int la = ((u >> 1) & 1) | ((u & 1) << 1);
;         const float wu = __builtin_bit_cast(float, __builtin_amdgcn_readlane(__builtin_bit_cast(int, ws), la));
;         const f32x2 w2 = {wu, wu};
;         const unsigned vw[2] = {vr[u].x, vr[u].y};
; #pragma unroll
;         for (int i = 0; i < 2; i++) {
;             acc[i * 4 + 0] = __builtin_elementwise_fma(w2, __builtin_amdgcn_cvt_scalef32_pk_f32_fp4(vw[i], 1.0f, 0), acc[i * 4 + 0]);
	v_dot8c_i32_i4_e32 v12, v82, v4
	v_dot8c_i32_i4_e32 v27, v82, v5
	v_dot8c_i32_i4_e32 v12, v83, v6
	v_dot8c_i32_i4_e32 v27, v83, v7
	v_mov_b32_e32 v76, v13
	v_dot8c_i32_i4_e32 v76, v84, v5
	v_dot8c_i32_i4_e32 v76, v85, v7
	v_lshl_add_u32 v12, v12, 4, v27
	v_mov_b32_e32 v27, v13
	v_dot8c_i32_i4_e32 v27, v84, v4
	v_dot8c_i32_i4_e32 v27, v85, v6
	v_mov_b32_e32 v77, v13
	v_dot8c_i32_i4_e32 v77, v74, v5
	v_dot8c_i32_i4_e32 v77, v75, v7
	v_lshl_add_u32 v27, v27, 4, v76
	v_mov_b32_e32 v76, v13
	v_dot8c_i32_i4_e32 v76, v74, v4
	v_dot8c_i32_i4_e32 v76, v75, v6
	v_mov_b32_e32 v75, v13
	v_dot8c_i32_i4_e32 v75, v80, v4
	v_mov_b32_e32 v4, v13
	v_dot8c_i32_i4_e32 v4, v80, v5
	v_dot8c_i32_i4_e32 v75, v81, v6
	v_dot8c_i32_i4_e32 v4, v81, v7
	v_lshl_add_u32 v74, v76, 4, v77
	v_cndmask_b32_e64 v6, v74, v12, s[0:1]
	v_cvt_scalef32_pk_f32_fp4 v[76:77], v72, 1.0 op_sel:[1,1,0]
	v_lshl_add_u32 v4, v75, 4, v4
	v_cndmask_b32_e64 v5, v27, v4, s[0:1]
	v_cndmask_b32_e64 v4, v4, v27, s[0:1]
	v_cvt_scalef32_pk_f32_fp4 v[78:79], v73, 1.0
	v_cvt_scalef32_pk_f32_fp4 v[80:81], v73, 1.0 op_sel:[1,0,0]
	v_add_u32_dpp v4, v4, v5 quad_perm:[1,0,3,2] row_mask:0xf bank_mask:0xf bound_ctrl:1
	v_cndmask_b32_e64 v5, v12, v74, s[0:1]
	v_cvt_scalef32_pk_f32_fp4 v[74:75], v72, 1.0 op_sel:[0,1,0]
	v_cvt_scalef32_pk_f32_fp4 v[82:83], v73, 1.0 op_sel:[0,1,0]
	v_add_u32_dpp v5, v6, v5 quad_perm:[1,0,3,2] row_mask:0xf bank_mask:0xf bound_ctrl:1
	v_cndmask_b32_e64 v6, v5, v4, s[2:3]
	v_cndmask_b32_e64 v4, v4, v5, s[2:3]
	v_cvt_scalef32_pk_f32_fp4 v[84:85], v70, 1.0
	v_lshl_add_u64 v[28:29], v[22:23], 0, v[28:29]
	v_add_u32_dpp v4, v4, v6 quad_perm:[2,3,0,1] row_mask:0xf bank_mask:0xf bound_ctrl:1
	v_mov_b32_e32 v27, v13
	v_cvt_scalef32_pk_f32_fp4 v[108:109], v62, 1.0 op_sel:[0,1,0]
	v_add_u32_dpp v4, v4, v4 row_ror:4 row_mask:0xf bank_mask:0xf bound_ctrl:1
	s_nop 1
	v_add_u32_dpp v4, v4, v4 row_ror:8 row_mask:0xf bank_mask:0xf bound_ctrl:1
	v_mov_b32_e32 v5, v4
	s_nop 1
	v_permlane16_swap_b32_e32 v4, v5
	v_add_u32_e32 v4, v4, v5
	v_mov_b32_e32 v5, v4
	s_nop 1
	v_permlane32_swap_b32_e32 v4, v5
	v_add_u32_e32 v4, v5, v4
	v_cvt_f32_i32_e32 v4, v4
	v_mul_f32_e32 v4, v105, v4
	v_fma_f32 v5, |v4|, s39, 1.0
	v_rcp_f32_e32 v5, v5
	v_mul_f32_e32 v7, v4, v4
	v_mul_f32_e32 v7, 0xbf38aa3b, v7
	v_exp_f32_e32 v7, v7
	v_fmamk_f32 v6, v5, 0x3f07dc22, v129
	v_fmaak_f32 v6, v5, v6, 0x3f35f0e3
	v_fmaak_f32 v6, v5, v6, 0xbe11a98e
	v_fmaak_f32 v6, v5, v6, 0x3e027906
	v_mul_f32_e32 v5, v5, v6
	v_mul_f32_e32 v5, v7, v5
	v_mul_f32_e32 v6, v4, v5
	v_fma_f32 v5, -v4, v5, v4
	v_cmp_gt_f32_e32 vcc, 0, v4
	s_nop 1
	v_cndmask_b32_e32 v4, v5, v6, vcc
	v_mul_f32_e32 v12, v104, v4
	v_cvt_scalef32_pk_f32_fp4 v[4:5], v72, 1.0
	v_readlane_b32 s4, v12, 0
	v_cvt_scalef32_pk_f32_fp4 v[6:7], v72, 1.0 op_sel:[1,0,0]
	v_cvt_scalef32_pk_f32_fp4 v[72:73], v73, 1.0 op_sel:[1,1,0]
	v_pk_fma_f32 v[4:5], s[4:5], v[4:5], v[100:101] op_sel_hi:[0,1,1]
	v_pk_fma_f32 v[6:7], s[4:5], v[6:7], v[98:99] op_sel_hi:[0,1,1]
	v_pk_fma_f32 v[74:75], s[4:5], v[74:75], v[96:97] op_sel_hi:[0,1,1]
	v_pk_fma_f32 v[76:77], s[4:5], v[76:77], v[94:95] op_sel_hi:[0,1,1]
	v_pk_fma_f32 v[78:79], s[4:5], v[78:79], v[92:93] op_sel_hi:[0,1,1]
	v_pk_fma_f32 v[80:81], s[4:5], v[80:81], v[90:91] op_sel_hi:[0,1,1]
	v_pk_fma_f32 v[82:83], s[4:5], v[82:83], v[88:89] op_sel_hi:[0,1,1]
	v_pk_fma_f32 v[72:73], s[4:5], v[72:73], v[86:87] op_sel_hi:[0,1,1]
	v_readlane_b32 s4, v12, 2
	s_nop 1
	v_pk_fma_f32 v[4:5], s[4:5], v[84:85], v[4:5] op_sel_hi:[0,1,1]
	v_cvt_scalef32_pk_f32_fp4 v[84:85], v70, 1.0 op_sel:[1,0,0]
	v_pk_fma_f32 v[84:85], s[4:5], v[84:85], v[6:7] op_sel_hi:[0,1,1]
	v_cvt_scalef32_pk_f32_fp4 v[6:7], v70, 1.0 op_sel:[0,1,0]
	v_pk_fma_f32 v[90:91], s[4:5], v[6:7], v[74:75] op_sel_hi:[0,1,1]
	v_cvt_scalef32_pk_f32_fp4 v[6:7], v70, 1.0 op_sel:[1,1,0]
	v_pk_fma_f32 v[92:93], s[4:5], v[6:7], v[76:77] op_sel_hi:[0,1,1]
	v_cvt_scalef32_pk_f32_fp4 v[6:7], v71, 1.0
	v_pk_fma_f32 v[94:95], s[4:5], v[6:7], v[78:79] op_sel_hi:[0,1,1]
	v_cvt_scalef32_pk_f32_fp4 v[6:7], v71, 1.0 op_sel:[1,0,0]
	v_pk_fma_f32 v[96:97], s[4:5], v[6:7], v[80:81] op_sel_hi:[0,1,1]
	v_cvt_scalef32_pk_f32_fp4 v[6:7], v71, 1.0 op_sel:[0,1,0]
	v_pk_fma_f32 v[98:99], s[4:5], v[6:7], v[82:83] op_sel_hi:[0,1,1]
	v_cvt_scalef32_pk_f32_fp4 v[6:7], v71, 1.0 op_sel:[1,1,0]
	v_pk_fma_f32 v[100:101], s[4:5], v[6:7], v[72:73] op_sel_hi:[0,1,1]
	v_ashrrev_i32_e32 v6, 11, v8
	v_mul_i32_i24_e32 v6, 0x1800, v6
	v_ashrrev_i32_e32 v7, 31, v6
	v_lshl_add_u64 v[6:7], v[6:7], 2, s[22:23]
	v_readlane_b32 s4, v12, 1
	global_load_dwordx4 v[70:73], v[28:29], off offset:16
	global_load_dwordx4 v[74:77], v[28:29], off
	v_lshl_add_u64 v[28:29], v[6:7], 0, v[26:27]
	v_cvt_scalef32_pk_f32_fp4 v[82:83], v62, 1.0
	v_add_co_u32_e32 v6, vcc, s40, v28
	v_pk_fma_f32 v[104:105], s[4:5], v[82:83], v[4:5] op_sel_hi:[0,1,1]
	v_cvt_scalef32_pk_f32_fp4 v[4:5], v62, 1.0 op_sel:[1,0,0]
	v_addc_co_u32_e32 v7, vcc, 0, v29, vcc
	v_pk_fma_f32 v[106:107], s[4:5], v[4:5], v[84:85] op_sel_hi:[0,1,1]
	v_lshl_add_u64 v[4:5], v[28:29], 0, s[30:31]
	v_pk_fma_f32 v[28:29], s[4:5], v[108:109], v[90:91] op_sel_hi:[0,1,1]
	v_cvt_scalef32_pk_f32_fp4 v[90:91], v62, 1.0 op_sel:[1,1,0]
	v_pk_fma_f32 v[108:109], s[4:5], v[90:91], v[92:93] op_sel_hi:[0,1,1]
	v_cvt_scalef32_pk_f32_fp4 v[90:91], v63, 1.0
	global_load_dwordx4 v[78:81], v[6:7], off
	v_pk_fma_f32 v[94:95], s[4:5], v[90:91], v[94:95] op_sel_hi:[0,1,1]
	v_cvt_scalef32_pk_f32_fp4 v[90:91], v63, 1.0 op_sel:[1,0,0]
	global_load_dwordx4 v[82:85], v[4:5], off offset:32
	global_load_dwordx4 v[86:89], v[4:5], off offset:16
	v_pk_fma_f32 v[96:97], s[4:5], v[90:91], v[96:97] op_sel_hi:[0,1,1]
	v_cvt_scalef32_pk_f32_fp4 v[90:91], v63, 1.0 op_sel:[0,1,0]
	v_cvt_scalef32_pk_f32_fp4 v[62:63], v63, 1.0 op_sel:[1,1,0]
	v_pk_fma_f32 v[98:99], s[4:5], v[90:91], v[98:99] op_sel_hi:[0,1,1]
	v_pk_fma_f32 v[62:63], s[4:5], v[62:63], v[100:101] op_sel_hi:[0,1,1]
	v_readlane_b32 s4, v12, 3
	s_waitcnt vmcnt(11)
; __device__ __forceinline__ float bf_lo(unsigned u) { return __uint_as_float(u << 16); }
; __device__ __forceinline__ void p3_dots(const u32x2 (&ur)[4], const unsigned* rec, int lane, int (&pt)[4]) {
;     const u32x4 qh = *(const u32x4*)(rec + 256 + lane * 4);
; #pragma unroll
;     for (int u = 0; u < 4; u++) {
;         const int w0 = (int)ur[u].x, w1 = (int)ur[u].y;
;         int dh = __builtin_amdgcn_sdot8(w0, (int)qh.x, 0, false);
;         dh = __builtin_amdgcn_sdot8(w1, (int)qh.z, dh, false);
;         int dl = __builtin_amdgcn_sdot8(w0, (int)qh.y, 0, false);
;         dl = __builtin_amdgcn_sdot8(w1, (int)qh.w, dl, false);
;         pt[u] = (dh << 4) + dl;
;     }
; }
; template <int CTRL> __device__ __forceinline__ int dpp_i(int v) { return __builtin_amdgcn_mov_dpp(v, CTRL, 0xF, 0xF, true); }
; __device__ __forceinline__ int xrow_sum_i(int v) {
;     const auto a = __builtin_amdgcn_permlane16_swap((unsigned)v, (unsigned)v, false, false);
;     v = (int)a[0] + (int)a[1];
;     const auto b = __builtin_amdgcn_permlane32_swap((unsigned)v, (unsigned)v, false, false);
;     return (int)b[0] + (int)b[1];
; }
; __device__ __forceinline__ float p3_weight(const int (&pt)[4], int lane, float sh, int hs8, const P3Sc& sc) {
;     int m2[2], m1;
;     const bool c0 = lane & 1;
; #pragma unroll
; __device__ __forceinline__ void p3_finish(const Params& p, float* dstp, int tok, int lane, const f32x2 (&acc)[8], float* tr) {
;     const float* mod = (const float*)(p.ws + OFF_MOD);
;     const int b = tok >> 11;
;     float own[16];
; #pragma unroll
;     for (int i = 0; i < 16; i++) own[i] = acc[i >> 1][i & 1];
;     const int d0 = lane * 16;
;     float x2[16];
;     float ss = 0.f;
;     const bf16_t* x1b = (const bf16_t*)(p.ws + OFF_X1B) + (size_t)tok * DM + d0;
;     const u32x4 xa = *(const u32x4*)x1b, xb = *(const u32x4*)(x1b + 8);
;     const unsigned xw[8] = {xa.x, xa.y, xa.z, xa.w, xb.x, xb.y, xb.z, xb.w};
; #pragma unroll
;     for (int i = 0; i < 4; i++) {
;         const int d = d0 + i * 4;
;         const f32x4 xv = {bf_lo(xw[2 * i]), bf_hi(xw[2 * i]), bf_lo(xw[2 * i + 1]), bf_hi(xw[2 * i + 1])};
;         const f32x4 gt = *(const f32x4*)(mod + b * 6144 + 5 * 1024 + d);
; #pragma unroll
;         for (int j = 0; j < 4; j++) { const float v = xv[j] + gt[j] * own[i * 4 + j]; x2[i * 4 + j] = v; ss += v * v; }
;     }
;     ss = wave_sum(ss);
	v_cvt_scalef32_pk_f32_fp4 v[90:91], v58, 1.0
	v_mov_b32_e32 v12, v13
	v_pk_fma_f32 v[100:101], s[4:5], v[90:91], v[104:105] op_sel_hi:[0,1,1]
	global_load_dwordx4 v[90:93], v[4:5], off offset:48
	v_cvt_scalef32_pk_f32_fp4 v[104:105], v58, 1.0 op_sel:[1,0,0]
	v_pk_fma_f32 v[104:105], s[4:5], v[104:105], v[106:107] op_sel_hi:[0,1,1]
	v_cvt_scalef32_pk_f32_fp4 v[106:107], v58, 1.0 op_sel:[0,1,0]
	v_pk_fma_f32 v[28:29], s[4:5], v[106:107], v[28:29] op_sel_hi:[0,1,1]
	v_cvt_scalef32_pk_f32_fp4 v[106:107], v58, 1.0 op_sel:[1,1,0]
	v_pk_fma_f32 v[106:107], s[4:5], v[106:107], v[108:109] op_sel_hi:[0,1,1]
	v_cvt_scalef32_pk_f32_fp4 v[108:109], v59, 1.0
	v_pk_fma_f32 v[94:95], s[4:5], v[108:109], v[94:95] op_sel_hi:[0,1,1]
	v_cvt_scalef32_pk_f32_fp4 v[108:109], v59, 1.0 op_sel:[1,0,0]
	s_waitcnt vmcnt(9)
	v_dot8c_i32_i4_e32 v12, v64, v0
	v_dot8c_i32_i4_e32 v27, v64, v1
	v_pk_fma_f32 v[96:97], s[4:5], v[108:109], v[96:97] op_sel_hi:[0,1,1]
	v_cvt_scalef32_pk_f32_fp4 v[108:109], v59, 1.0 op_sel:[0,1,0]
	v_cvt_scalef32_pk_f32_fp4 v[58:59], v59, 1.0 op_sel:[1,1,0]
	v_dot8c_i32_i4_e32 v12, v65, v2
	v_dot8c_i32_i4_e32 v27, v65, v3
	v_pk_fma_f32 v[98:99], s[4:5], v[108:109], v[98:99] op_sel_hi:[0,1,1]
	v_pk_fma_f32 v[108:109], s[4:5], v[58:59], v[62:63] op_sel_hi:[0,1,1]
	v_mov_b32_e32 v58, v13
	v_lshl_add_u32 v12, v12, 4, v27
	v_mov_b32_e32 v27, v13
	v_dot8c_i32_i4_e32 v27, v68, v0
	v_dot8c_i32_i4_e32 v58, v68, v1
	v_dot8c_i32_i4_e32 v27, v69, v2
	v_dot8c_i32_i4_e32 v58, v69, v3
	v_mov_b32_e32 v59, v13
	s_waitcnt vmcnt(7)
	v_dot8c_i32_i4_e32 v59, v60, v1
	v_dot8c_i32_i4_e32 v59, v61, v3
	v_lshl_add_u32 v27, v27, 4, v58
	v_mov_b32_e32 v58, v13
	v_dot8c_i32_i4_e32 v58, v60, v0
	v_dot8c_i32_i4_e32 v58, v61, v2
	s_waitcnt vmcnt(4)
	v_lshlrev_b32_e32 v110, 16, v74
	s_nop 0
	v_lshl_add_u32 v58, v58, 4, v59
	v_mov_b32_e32 v59, v13
	v_dot8c_i32_i4_e32 v59, v66, v0
	v_mov_b32_e32 v0, v13
	v_dot8c_i32_i4_e32 v0, v66, v1
	v_dot8c_i32_i4_e32 v59, v67, v2
	v_dot8c_i32_i4_e32 v0, v67, v3
	v_cndmask_b32_e64 v2, v58, v12, s[0:1]
	v_and_b32_e32 v111, 0xffff0000, v74
	v_lshlrev_b32_e32 v74, 16, v75
	v_lshl_add_u32 v0, v59, 4, v0
	v_cndmask_b32_e64 v1, v27, v0, s[0:1]
	v_cndmask_b32_e64 v0, v0, v27, s[0:1]
	v_and_b32_e32 v75, 0xffff0000, v75
	s_waitcnt vmcnt(3)
	v_pk_fma_f32 v[74:75], v[104:105], v[80:81], v[74:75]
	v_add_u32_dpp v0, v0, v1 quad_perm:[1,0,3,2] row_mask:0xf bank_mask:0xf bound_ctrl:1
	v_cndmask_b32_e64 v1, v12, v58, s[0:1]
	v_lshlrev_b32_e32 v104, 16, v76
	v_and_b32_e32 v105, 0xffff0000, v76
	v_add_u32_dpp v1, v2, v1 quad_perm:[1,0,3,2] row_mask:0xf bank_mask:0xf bound_ctrl:1
	v_cndmask_b32_e64 v12, v1, v0, s[2:3]
	v_cndmask_b32_e64 v27, v0, v1, s[2:3]
	global_load_dwordx4 v[0:3], v[24:25], off offset:48
	global_load_dwordx4 v[58:61], v[24:25], off offset:32
	global_load_dwordx4 v[62:65], v[24:25], off offset:16
	global_load_dwordx4 v[66:69], v[24:25], off
	v_pk_fma_f32 v[78:79], v[100:101], v[78:79], v[110:111]
	s_waitcnt vmcnt(5)
	v_pk_fma_f32 v[28:29], v[28:29], v[86:87], v[104:105]
	v_lshlrev_b32_e32 v104, 16, v70
	v_and_b32_e32 v105, 0xffff0000, v70
	v_lshlrev_b32_e32 v70, 16, v71
	v_and_b32_e32 v71, 0xffff0000, v71
	v_pk_mul_f32 v[100:101], v[78:79], v[78:79]
	v_pk_fma_f32 v[70:71], v[96:97], v[84:85], v[70:71]
	v_lshlrev_b32_e32 v96, 16, v72
	v_and_b32_e32 v97, 0xffff0000, v72
	v_pk_mul_f32 v[80:81], v[74:75], v[74:75]
	s_waitcnt vmcnt(4)
	v_pk_fma_f32 v[90:91], v[98:99], v[90:91], v[96:97]
	v_add_f32_e32 v98, v100, v101
	v_add_f32_e32 v80, v80, v98
	v_pk_mul_f32 v[86:87], v[28:29], v[28:29]
	v_lshlrev_b32_e32 v76, 16, v77
	v_and_b32_e32 v77, 0xffff0000, v77
	v_add_f32_e32 v80, v81, v80
	v_pk_fma_f32 v[76:77], v[106:107], v[88:89], v[76:77]
	v_add_f32_e32 v80, v86, v80
	v_pk_mul_f32 v[88:89], v[76:77], v[76:77]
	v_add_f32_e32 v80, v87, v80
	v_pk_fma_f32 v[82:83], v[94:95], v[82:83], v[104:105]
	v_add_f32_e32 v80, v88, v80
	v_pk_mul_f32 v[94:95], v[82:83], v[82:83]
	v_add_f32_e32 v80, v89, v80
	v_add_f32_e32 v80, v94, v80
	v_pk_mul_f32 v[84:85], v[70:71], v[70:71]
	v_add_f32_e32 v80, v95, v80
	v_add_f32_e32 v80, v84, v80
	v_pk_mul_f32 v[96:97], v[90:91], v[90:91]
	v_lshlrev_b32_e32 v72, 16, v73
	v_and_b32_e32 v73, 0xffff0000, v73
	v_add_f32_e32 v80, v85, v80
	v_pk_fma_f32 v[72:73], v[108:109], v[92:93], v[72:73]
	v_add_f32_e32 v80, v96, v80
	v_pk_mul_f32 v[92:93], v[72:73], v[72:73]
	v_add_f32_e32 v80, v97, v80
	v_add_f32_e32 v80, v92, v80
	v_add_f32_e32 v80, v93, v80
	ds_bpermute_b32 v81, v112, v80
	v_add_u32_dpp v12, v27, v12 quad_perm:[2,3,0,1] row_mask:0xf bank_mask:0xf bound_ctrl:1
	s_waitcnt lgkmcnt(0)
	v_add_f32_e32 v80, v80, v81
	ds_bpermute_b32 v81, v113, v80
	v_add_u32_dpp v12, v12, v12 row_ror:4 row_mask:0xf bank_mask:0xf bound_ctrl:1
	s_waitcnt lgkmcnt(0)
	v_add_f32_e32 v80, v80, v81
	v_add_u32_dpp v12, v12, v12 row_ror:8 row_mask:0xf bank_mask:0xf bound_ctrl:1
	v_mov_b32_e32 v27, v12
	ds_bpermute_b32 v81, v114, v80
	s_nop 0
	v_permlane16_swap_b32_e32 v12, v27
	v_add_u32_e32 v12, v12, v27
	v_mov_b32_e32 v27, v12
	s_nop 1
	v_permlane32_swap_b32_e32 v12, v27
	v_add_u32_e32 v12, v27, v12
	s_waitcnt lgkmcnt(0)
	v_add_f32_e32 v27, v80, v81
	ds_bpermute_b32 v80, v115, v27
	v_cvt_f32_i32_e32 v12, v12
	s_waitcnt lgkmcnt(0)
	v_add_f32_e32 v27, v27, v80
	ds_bpermute_b32 v80, v116, v27
	v_mul_f32_e32 v81, v103, v12
	v_fma_f32 v12, |v81|, s39, 1.0
	v_rcp_f32_e32 v12, v12
	s_waitcnt lgkmcnt(0)
	v_add_f32_e32 v27, v27, v80
	ds_bpermute_b32 v80, v117, v27
	v_fmamk_f32 v84, v12, 0x3f07dc22, v129
	v_fmaak_f32 v84, v12, v84, 0x3f35f0e3
	v_fmaak_f32 v84, v12, v84, 0xbe11a98e
	v_fmaak_f32 v84, v12, v84, 0x3e027906
	s_waitcnt lgkmcnt(0)
; __device__ __forceinline__ void p3_axpy(const u32x2 (&vr)[4], float ws, f32x2 (&acc)[8]) {
; #pragma unroll
;     for (int u = 0; u < 4; u++) {
;         const int la = ((u >> 1) & 1) | ((u & 1) << 1);
;         const float wu = __builtin_bit_cast(float, __builtin_amdgcn_readlane(__builtin_bit_cast(int, ws), la));
;         const f32x2 w2 = {wu, wu};
;         const unsigned vw[2] = {vr[u].x, vr[u].y};
; #pragma unroll
;         for (int i = 0; i < 2; i++) {
;             acc[i * 4 + 0] = __builtin_elementwise_fma(w2, __builtin_amdgcn_cvt_scalef32_pk_f32_fp4(vw[i], 1.0f, 0), acc[i * 4 + 0]);
;             acc[i * 4 + 1] = __builtin_elementwise_fma(w2, __builtin_amdgcn_cvt_scalef32_pk_f32_fp4(vw[i], 1.0f, 1), acc[i * 4 + 1]);
;             acc[i * 4 + 2] = __builtin_elementwise_fma(w2, __builtin_amdgcn_cvt_scalef32_pk_f32_fp4(vw[i], 1.0f, 2), acc[i * 4 + 2]);
;             acc[i * 4 + 3] = __builtin_elementwise_fma(w2, __builtin_amdgcn_cvt_scalef32_pk_f32_fp4(vw[i], 1.0f, 3), acc[i * 4 + 3]);
;         }
;     }
; }
; __device__ __forceinline__ void p3_finish(const Params& p, float* dstp, int tok, int lane, const f32x2 (&acc)[8], float* tr) {
;     ...
;     ss = wave_sum(ss);
;     const float rstd = rsqrtf(ss * (1.f / 1024.f) + 1e-6f);
; #pragma unroll
;     for (int i = 0; i < 4; i++) {
;         const int d = d0 + i * 4;
;         const f32x4 fg = *(const f32x4*)(p.final_g + d);
;         f32x4 o;
; #pragma unroll
;         for (int j = 0; j < 4; j++) o[j] = x2[i * 4 + j] * rstd * fg[j];
;         *(f32x4*)(tr + d) = o;
;     }
;     __builtin_amdgcn_fence(__ATOMIC_RELEASE, "wavefront");
;     __builtin_amdgcn_wave_barrier();
;     __builtin_amdgcn_fence(__ATOMIC_ACQUIRE, "wavefront");
; #pragma unroll
;     for (int j = 0; j < 4; j++) {
;         const f32x4 v = *(const f32x4*)(tr + j * 256 + lane * 4);
;         *(f32x4*)(dstp + (size_t)tok * DM + j * 256 + lane * 4) = v;
;     }
;     __builtin_amdgcn_wave_barrier();
; }
	v_add_f32_e32 v27, v27, v80
	v_mul_f32_e32 v12, v12, v84
	v_mul_f32_e32 v84, v81, v81
	v_fmamk_f32 v27, v27, 0x3a800000, v130
	v_mul_f32_e32 v84, 0xbf38aa3b, v84
	v_mul_f32_e32 v80, 0x4b800000, v27
	v_cmp_gt_f32_e32 vcc, s38, v27
	v_exp_f32_e32 v84, v84
	s_nop 0
	v_cndmask_b32_e32 v27, v27, v80, vcc
	v_rsq_f32_e32 v27, v27
	v_mul_f32_e32 v12, v84, v12
	v_mul_f32_e32 v80, v81, v12
	v_fma_f32 v84, -v81, v12, v81
	v_mul_f32_e32 v12, 0x45800000, v27
	v_cndmask_b32_e32 v12, v27, v12, vcc
	v_pk_mul_f32 v[78:79], v[78:79], v[12:13] op_sel_hi:[1,0]
	v_pk_mul_f32 v[74:75], v[74:75], v[12:13] op_sel_hi:[1,0]
	s_waitcnt vmcnt(0)
	v_pk_mul_f32 v[66:67], v[66:67], v[78:79]
	v_pk_mul_f32 v[68:69], v[68:69], v[74:75]
	ds_write_b128 v118, v[66:69]
	v_pk_mul_f32 v[28:29], v[28:29], v[12:13] op_sel_hi:[1,0]
	v_pk_mul_f32 v[66:67], v[76:77], v[12:13] op_sel_hi:[1,0]
	v_pk_mul_f32 v[62:63], v[62:63], v[28:29]
	v_pk_mul_f32 v[64:65], v[64:65], v[66:67]
	ds_write_b128 v118, v[62:65] offset:16
	v_pk_mul_f32 v[28:29], v[82:83], v[12:13] op_sel_hi:[1,0]
	v_pk_mul_f32 v[62:63], v[70:71], v[12:13] op_sel_hi:[1,0]
	v_pk_mul_f32 v[58:59], v[58:59], v[28:29]
	v_pk_mul_f32 v[60:61], v[60:61], v[62:63]
	ds_write_b128 v118, v[58:61] offset:32
	v_pk_mul_f32 v[28:29], v[90:91], v[12:13] op_sel_hi:[1,0]
	v_pk_mul_f32 v[58:59], v[72:73], v[12:13] op_sel_hi:[1,0]
	v_pk_mul_f32 v[0:1], v[0:1], v[28:29]
	v_pk_mul_f32 v[2:3], v[2:3], v[58:59]
	ds_write_b128 v118, v[0:3] offset:48
	ds_read_b128 v[0:3], v128
	ds_read_b128 v[58:61], v128 offset:1024
	ds_read_b128 v[62:65], v128 offset:2048
	ds_read_b128 v[66:69], v128 offset:3072
	v_lshlrev_b64 v[28:29], 12, v[8:9]
	v_lshl_add_u64 v[28:29], v[18:19], 0, v[28:29]
	s_waitcnt lgkmcnt(3)
	global_store_dwordx4 v[28:29], v[0:3], off
	s_waitcnt lgkmcnt(2)
	global_store_dwordx4 v[28:29], v[58:61], off offset:1024
	s_waitcnt lgkmcnt(1)
	global_store_dwordx4 v[28:29], v[62:65], off offset:2048
	s_waitcnt lgkmcnt(0)
	global_store_dwordx4 v[28:29], v[66:69], off offset:3072
	v_lshl_add_u64 v[28:29], v[22:23], 0, v[32:33]
	global_load_dwordx4 v[0:3], v[28:29], off offset:16
	global_load_dwordx4 v[58:61], v[28:29], off
	global_load_dwordx4 v[62:65], v[6:7], off
	v_cmp_gt_f32_e32 vcc, 0, v81
	global_load_dwordx4 v[66:69], v[4:5], off offset:32
	global_load_dwordx4 v[70:73], v[4:5], off offset:16
	v_cndmask_b32_e32 v6, v84, v80, vcc
	v_mul_f32_e32 v9, v102, v6
	v_cvt_scalef32_pk_f32_fp4 v[6:7], v40, 1.0
	v_readlane_b32 s4, v9, 0
	v_add_u32_e32 v8, s36, v8
	s_waitcnt vmcnt(3)
	v_lshlrev_b32_e32 v78, 16, v58
	v_pk_fma_f32 v[28:29], s[4:5], v[6:7], v[52:53] op_sel_hi:[0,1,1]
	v_cvt_scalef32_pk_f32_fp4 v[6:7], v40, 1.0 op_sel:[1,0,0]
	v_pk_fma_f32 v[32:33], s[4:5], v[6:7], v[50:51] op_sel_hi:[0,1,1]
	v_cvt_scalef32_pk_f32_fp4 v[6:7], v40, 1.0 op_sel:[0,1,0]
	v_pk_fma_f32 v[48:49], s[4:5], v[6:7], v[48:49] op_sel_hi:[0,1,1]
	v_cvt_scalef32_pk_f32_fp4 v[6:7], v40, 1.0 op_sel:[1,1,0]
	v_pk_fma_f32 v[46:47], s[4:5], v[6:7], v[46:47] op_sel_hi:[0,1,1]
	v_cvt_scalef32_pk_f32_fp4 v[6:7], v41, 1.0
	v_pk_fma_f32 v[44:45], s[4:5], v[6:7], v[44:45] op_sel_hi:[0,1,1]
	v_cvt_scalef32_pk_f32_fp4 v[6:7], v41, 1.0 op_sel:[1,0,0]
	v_pk_fma_f32 v[42:43], s[4:5], v[6:7], v[42:43] op_sel_hi:[0,1,1]
	v_cvt_scalef32_pk_f32_fp4 v[6:7], v41, 1.0 op_sel:[0,1,0]
	v_pk_fma_f32 v[50:51], s[4:5], v[6:7], v[54:55] op_sel_hi:[0,1,1]
	v_cvt_scalef32_pk_f32_fp4 v[6:7], v41, 1.0 op_sel:[1,1,0]
	v_pk_fma_f32 v[40:41], s[4:5], v[6:7], v[56:57] op_sel_hi:[0,1,1]
	global_load_dwordx4 v[4:7], v[4:5], off offset:48
	v_readlane_b32 s4, v9, 2
	v_cvt_scalef32_pk_f32_fp4 v[52:53], v38, 1.0
	v_and_b32_e32 v79, 0xffff0000, v58
	v_pk_fma_f32 v[28:29], s[4:5], v[52:53], v[28:29] op_sel_hi:[0,1,1]
	v_cvt_scalef32_pk_f32_fp4 v[52:53], v38, 1.0 op_sel:[1,0,0]
	v_pk_fma_f32 v[32:33], s[4:5], v[52:53], v[32:33] op_sel_hi:[0,1,1]
	v_cvt_scalef32_pk_f32_fp4 v[52:53], v38, 1.0 op_sel:[0,1,0]
	v_pk_fma_f32 v[48:49], s[4:5], v[52:53], v[48:49] op_sel_hi:[0,1,1]
	v_cvt_scalef32_pk_f32_fp4 v[52:53], v38, 1.0 op_sel:[1,1,0]
	v_pk_fma_f32 v[46:47], s[4:5], v[52:53], v[46:47] op_sel_hi:[0,1,1]
	v_cvt_scalef32_pk_f32_fp4 v[52:53], v39, 1.0
	v_pk_fma_f32 v[44:45], s[4:5], v[52:53], v[44:45] op_sel_hi:[0,1,1]
	v_cvt_scalef32_pk_f32_fp4 v[52:53], v39, 1.0 op_sel:[1,0,0]
	v_pk_fma_f32 v[42:43], s[4:5], v[52:53], v[42:43] op_sel_hi:[0,1,1]
	v_cvt_scalef32_pk_f32_fp4 v[52:53], v39, 1.0 op_sel:[0,1,0]
	v_cvt_scalef32_pk_f32_fp4 v[38:39], v39, 1.0 op_sel:[1,1,0]
	v_pk_fma_f32 v[50:51], s[4:5], v[52:53], v[50:51] op_sel_hi:[0,1,1]
	v_pk_fma_f32 v[38:39], s[4:5], v[38:39], v[40:41] op_sel_hi:[0,1,1]
	v_readlane_b32 s4, v9, 1
	v_cvt_scalef32_pk_f32_fp4 v[40:41], v36, 1.0
	v_lshlrev_b32_e32 v58, 16, v59
	v_pk_fma_f32 v[28:29], s[4:5], v[40:41], v[28:29] op_sel_hi:[0,1,1]
	v_cvt_scalef32_pk_f32_fp4 v[40:41], v36, 1.0 op_sel:[1,0,0]
	v_pk_fma_f32 v[32:33], s[4:5], v[40:41], v[32:33] op_sel_hi:[0,1,1]
	v_cvt_scalef32_pk_f32_fp4 v[40:41], v36, 1.0 op_sel:[0,1,0]
	v_pk_fma_f32 v[40:41], s[4:5], v[40:41], v[48:49] op_sel_hi:[0,1,1]
	v_cvt_scalef32_pk_f32_fp4 v[48:49], v36, 1.0 op_sel:[1,1,0]
	v_pk_fma_f32 v[46:47], s[4:5], v[48:49], v[46:47] op_sel_hi:[0,1,1]
	v_cvt_scalef32_pk_f32_fp4 v[48:49], v37, 1.0
	v_pk_fma_f32 v[44:45], s[4:5], v[48:49], v[44:45] op_sel_hi:[0,1,1]
	v_cvt_scalef32_pk_f32_fp4 v[48:49], v37, 1.0 op_sel:[1,0,0]
	v_pk_fma_f32 v[42:43], s[4:5], v[48:49], v[42:43] op_sel_hi:[0,1,1]
	v_cvt_scalef32_pk_f32_fp4 v[48:49], v37, 1.0 op_sel:[0,1,0]
	v_cvt_scalef32_pk_f32_fp4 v[36:37], v37, 1.0 op_sel:[1,1,0]
	v_pk_fma_f32 v[48:49], s[4:5], v[48:49], v[50:51] op_sel_hi:[0,1,1]
	v_pk_fma_f32 v[36:37], s[4:5], v[36:37], v[38:39] op_sel_hi:[0,1,1]
	v_readlane_b32 s4, v9, 3
	v_cvt_scalef32_pk_f32_fp4 v[38:39], v34, 1.0
	v_and_b32_e32 v59, 0xffff0000, v59
	v_pk_fma_f32 v[28:29], s[4:5], v[38:39], v[28:29] op_sel_hi:[0,1,1]
	v_cvt_scalef32_pk_f32_fp4 v[38:39], v34, 1.0 op_sel:[1,0,0]
	v_pk_fma_f32 v[50:51], s[4:5], v[38:39], v[32:33] op_sel_hi:[0,1,1]
	v_cvt_scalef32_pk_f32_fp4 v[32:33], v34, 1.0 op_sel:[0,1,0]
	v_pk_fma_f32 v[52:53], s[4:5], v[32:33], v[40:41] op_sel_hi:[0,1,1]
	v_cvt_scalef32_pk_f32_fp4 v[32:33], v34, 1.0 op_sel:[1,1,0]
	v_pk_fma_f32 v[54:55], s[4:5], v[32:33], v[46:47] op_sel_hi:[0,1,1]
	v_cvt_scalef32_pk_f32_fp4 v[32:33], v35, 1.0
	v_pk_fma_f32 v[56:57], s[4:5], v[32:33], v[44:45] op_sel_hi:[0,1,1]
	v_cvt_scalef32_pk_f32_fp4 v[32:33], v35, 1.0 op_sel:[1,0,0]
	v_pk_fma_f32 v[74:75], s[4:5], v[32:33], v[42:43] op_sel_hi:[0,1,1]
	v_cvt_scalef32_pk_f32_fp4 v[32:33], v35, 1.0 op_sel:[0,1,0]
	v_pk_fma_f32 v[48:49], s[4:5], v[32:33], v[48:49] op_sel_hi:[0,1,1]
	v_cvt_scalef32_pk_f32_fp4 v[32:33], v35, 1.0 op_sel:[1,1,0]
	v_pk_fma_f32 v[76:77], s[4:5], v[32:33], v[36:37] op_sel_hi:[0,1,1]
	global_load_dwordx4 v[32:35], v[24:25], off offset:48
	global_load_dwordx4 v[36:39], v[24:25], off offset:32
	global_load_dwordx4 v[40:43], v[24:25], off offset:16
	global_load_dwordx4 v[44:47], v[24:25], off
	s_waitcnt vmcnt(7)
; __device__ __forceinline__ float bf_lo(unsigned u) { return __uint_as_float(u << 16); }
; __device__ __forceinline__ float bf_hi(unsigned u) { return __uint_as_float(u & 0xffff0000u); }
; __device__ __forceinline__ void p3_finish(const Params& p, float* dstp, int tok, int lane, const f32x2 (&acc)[8], float* tr) {
;     const float* mod = (const float*)(p.ws + OFF_MOD);
;     const int b = tok >> 11;
;     float own[16];
; #pragma unroll
;     for (int i = 0; i < 16; i++) own[i] = acc[i >> 1][i & 1];
;     const int d0 = lane * 16;
;     float x2[16];
;     float ss = 0.f;
;     const bf16_t* x1b = (const bf16_t*)(p.ws + OFF_X1B) + (size_t)tok * DM + d0;
;     const u32x4 xa = *(const u32x4*)x1b, xb = *(const u32x4*)(x1b + 8);
;     const unsigned xw[8] = {xa.x, xa.y, xa.z, xa.w, xb.x, xb.y, xb.z, xb.w};
; #pragma unroll
;     for (int i = 0; i < 4; i++) {
;         const int d = d0 + i * 4;
;         const f32x4 xv = {bf_lo(xw[2 * i]), bf_hi(xw[2 * i]), bf_lo(xw[2 * i + 1]), bf_hi(xw[2 * i + 1])};
;         const f32x4 gt = *(const f32x4*)(mod + b * 6144 + 5 * 1024 + d);
; #pragma unroll
;         for (int j = 0; j < 4; j++) { const float v = xv[j] + gt[j] * own[i * 4 + j]; x2[i * 4 + j] = v; ss += v * v; }
;     }
;     ss = wave_sum(ss);
;     const float rstd = rsqrtf(ss * (1.f / 1024.f) + 1e-6f);
; #pragma unroll
;     for (int i = 0; i < 4; i++) {
;         const int d = d0 + i * 4;
;         const f32x4 fg = *(const f32x4*)(p.final_g + d);
;         f32x4 o;
; #pragma unroll
;         for (int j = 0; j < 4; j++) o[j] = x2[i * 4 + j] * rstd * fg[j];
;         *(f32x4*)(tr + d) = o;
;     }
;     __builtin_amdgcn_fence(__ATOMIC_RELEASE, "wavefront");
;     __builtin_amdgcn_wave_barrier();
;     __builtin_amdgcn_fence(__ATOMIC_ACQUIRE, "wavefront");
; #pragma unroll
;     for (int j = 0; j < 4; j++) {
;         const f32x4 v = *(const f32x4*)(tr + j * 256 + lane * 4);
;         *(f32x4*)(dstp + (size_t)tok * DM + j * 256 + lane * 4) = v;
;     }
;     __builtin_amdgcn_wave_barrier();
; }
	v_pk_fma_f32 v[28:29], v[28:29], v[62:63], v[78:79]
	v_pk_fma_f32 v[50:51], v[50:51], v[64:65], v[58:59]
	v_pk_mul_f32 v[62:63], v[28:29], v[28:29]
	v_pk_mul_f32 v[58:59], v[50:51], v[50:51]
	v_lshlrev_b32_e32 v64, 16, v60
	v_and_b32_e32 v65, 0xffff0000, v60
	v_add_f32_e32 v9, v62, v63
	s_waitcnt vmcnt(5)
	v_pk_fma_f32 v[52:53], v[52:53], v[70:71], v[64:65]
	v_add_f32_e32 v9, v58, v9
	v_pk_mul_f32 v[64:65], v[52:53], v[52:53]
	v_lshlrev_b32_e32 v60, 16, v61
	v_and_b32_e32 v61, 0xffff0000, v61
	v_add_f32_e32 v9, v59, v9
	v_pk_fma_f32 v[54:55], v[54:55], v[72:73], v[60:61]
	v_add_f32_e32 v9, v64, v9
	v_pk_mul_f32 v[60:61], v[54:55], v[54:55]
	v_lshlrev_b32_e32 v70, 16, v0
	v_and_b32_e32 v71, 0xffff0000, v0
	v_add_f32_e32 v9, v65, v9
	v_pk_fma_f32 v[56:57], v[56:57], v[66:67], v[70:71]
	v_add_f32_e32 v9, v60, v9
	v_pk_mul_f32 v[66:67], v[56:57], v[56:57]
	v_lshlrev_b32_e32 v0, 16, v1
	v_and_b32_e32 v1, 0xffff0000, v1
	v_add_f32_e32 v9, v61, v9
	v_pk_fma_f32 v[68:69], v[74:75], v[68:69], v[0:1]
	v_add_f32_e32 v9, v66, v9
	v_pk_mul_f32 v[0:1], v[68:69], v[68:69]
	v_lshlrev_b32_e32 v70, 16, v2
	v_and_b32_e32 v71, 0xffff0000, v2
	v_add_f32_e32 v9, v67, v9
	s_waitcnt vmcnt(4)
	v_pk_fma_f32 v[4:5], v[48:49], v[4:5], v[70:71]
	v_add_f32_e32 v0, v0, v9
	v_pk_mul_f32 v[48:49], v[4:5], v[4:5]
	v_lshlrev_b32_e32 v2, 16, v3
	v_and_b32_e32 v3, 0xffff0000, v3
	v_add_f32_e32 v0, v1, v0
	v_pk_fma_f32 v[6:7], v[76:77], v[6:7], v[2:3]
	v_add_f32_e32 v0, v48, v0
	v_pk_mul_f32 v[2:3], v[6:7], v[6:7]
	v_add_f32_e32 v0, v49, v0
	v_add_f32_e32 v0, v2, v0
	v_add_f32_e32 v0, v3, v0
	ds_bpermute_b32 v1, v112, v0
	s_waitcnt lgkmcnt(0)
	v_add_f32_e32 v0, v0, v1
	ds_bpermute_b32 v1, v113, v0
	s_waitcnt lgkmcnt(0)
	v_add_f32_e32 v0, v0, v1
	ds_bpermute_b32 v1, v114, v0
	s_waitcnt lgkmcnt(0)
	v_add_f32_e32 v0, v0, v1
	ds_bpermute_b32 v1, v115, v0
	s_waitcnt lgkmcnt(0)
	v_add_f32_e32 v0, v0, v1
	ds_bpermute_b32 v1, v116, v0
	s_waitcnt lgkmcnt(0)
	v_add_f32_e32 v0, v0, v1
	ds_bpermute_b32 v1, v117, v0
	s_waitcnt lgkmcnt(0)
	v_add_f32_e32 v0, v0, v1
	v_fmamk_f32 v0, v0, 0x3a800000, v130
	v_mul_f32_e32 v1, 0x4b800000, v0
	v_cmp_gt_f32_e32 vcc, s38, v0
	s_nop 1
	v_cndmask_b32_e32 v0, v0, v1, vcc
	v_rsq_f32_e32 v0, v0
	s_nop 0
	v_mul_f32_e32 v1, 0x45800000, v0
	v_cndmask_b32_e32 v12, v0, v1, vcc
	v_pk_mul_f32 v[0:1], v[28:29], v[12:13] op_sel_hi:[1,0]
	v_pk_mul_f32 v[2:3], v[50:51], v[12:13] op_sel_hi:[1,0]
	s_waitcnt vmcnt(0)
	v_pk_mul_f32 v[0:1], v[44:45], v[0:1]
	v_pk_mul_f32 v[2:3], v[46:47], v[2:3]
	ds_write_b128 v118, v[0:3]
	v_pk_mul_f32 v[0:1], v[52:53], v[12:13] op_sel_hi:[1,0]
	v_pk_mul_f32 v[2:3], v[54:55], v[12:13] op_sel_hi:[1,0]
	v_pk_mul_f32 v[0:1], v[40:41], v[0:1]
	v_pk_mul_f32 v[2:3], v[42:43], v[2:3]
	ds_write_b128 v118, v[0:3] offset:16
	v_pk_mul_f32 v[0:1], v[56:57], v[12:13] op_sel_hi:[1,0]
	v_pk_mul_f32 v[2:3], v[68:69], v[12:13] op_sel_hi:[1,0]
	v_pk_mul_f32 v[0:1], v[36:37], v[0:1]
	v_pk_mul_f32 v[2:3], v[38:39], v[2:3]
	ds_write_b128 v118, v[0:3] offset:32
	v_pk_mul_f32 v[0:1], v[4:5], v[12:13] op_sel_hi:[1,0]
	v_pk_mul_f32 v[2:3], v[6:7], v[12:13] op_sel_hi:[1,0]
	v_pk_mul_f32 v[0:1], v[32:33], v[0:1]
	v_pk_mul_f32 v[2:3], v[34:35], v[2:3]
	ds_write_b128 v118, v[0:3] offset:48
	ds_read_b128 v[0:3], v128
	ds_read_b128 v[4:7], v128 offset:1024
	v_lshlrev_b64 v[32:33], 12, v[30:31]
	v_lshl_add_u64 v[32:33], v[18:19], 0, v[32:33]
	ds_read_b128 v[28:31], v128 offset:2048
	s_waitcnt lgkmcnt(2)
	global_store_dwordx4 v[32:33], v[0:3], off
	s_waitcnt lgkmcnt(1)
	global_store_dwordx4 v[32:33], v[4:7], off offset:1024
	ds_read_b128 v[0:3], v128 offset:3072
	v_cmp_lt_i32_e32 vcc, s41, v8
	s_or_b64 s[28:29], vcc, s[28:29]
	s_waitcnt lgkmcnt(1)
	global_store_dwordx4 v[32:33], v[28:31], off offset:2048
	s_waitcnt lgkmcnt(0)
	global_store_dwordx4 v[32:33], v[0:3], off offset:3072
	s_andn2_b64 exec, exec, s[28:29]
	s_cbranch_execnz .LBB0_1042
